# grid barrier: flattened release (last arriver bumps every XCD generation) + L1 invalidate issued at arrival, 16 of 21 barriers
# speedup vs baseline: 1.0490x; 1.0346x over previous
.LBB0_1116:
	s_load_dwordx2 s[66:67], s[86:87], 0x110
	s_waitcnt lgkmcnt(0)
	s_cmp_gt_i32 s67, 3
	s_cbranch_scc0 .LBB0_1166
	s_waitcnt vmcnt(0)
	s_waitcnt vmcnt(63) expcnt(7) lgkmcnt(15)
	s_barrier
	s_mov_b64 s[4:5], exec
	v_readlane_b32 s2, v251, 3
	v_readlane_b32 s3, v251, 4
	s_and_b64 s[2:3], s[4:5], s[2:3]
	s_mov_b64 exec, s[2:3]
	s_cbranch_execz .Lxb_done_3
	v_mov_b32_e32 v0, 0
	s_waitcnt vmcnt(0) expcnt(0) lgkmcnt(0)
	ds_read_b32 v2, v0
	ds_read_b32 v1, v0 offset:4
	v_readlane_b32 s0, v251, 2
	v_readlane_b32 s6, v251, 5
	v_readlane_b32 s7, v251, 6
	s_lshl_b32 s0, s0, 8
	s_add_u32 s8, s6, s0
	s_addc_u32 s9, s7, 0
	v_mov_b32_e32 v3, 1
	v_mov_b32_e32 v4, 0x1000
	s_nop 4
	global_atomic_add v3, v4, v3, s[8:9] offset:1024 sc0
	buffer_inv sc1
	s_sub_u32 s10, 2, s66
	s_add_u32 s11, s10, 1
	s_waitcnt lgkmcnt(0)
	v_readfirstlane_b32 s12, v2
	v_readfirstlane_b32 s13, v1
	s_mul_i32 s14, s12, s11
	s_mul_i32 s15, s13, s11
	s_waitcnt vmcnt(0)
	v_readfirstlane_b32 s16, v3
	s_add_u32 s16, s16, 1
	s_cmp_lg_u32 s16, s14
	s_cbranch_scc1 .Lxb_wait_3
	buffer_wbl2 sc1
	s_waitcnt vmcnt(0)
	v_mov_b32_e32 v3, 1
	v_mov_b32_e32 v4, 0x7f000
	global_atomic_add v3, v4, v3, s[30:31] offset:1024 sc0
	s_waitcnt vmcnt(0)
	v_readfirstlane_b32 s16, v3
	s_add_u32 s16, s16, 1
	s_cmp_lg_u32 s16, s15
	s_cbranch_scc1 .Lxb_wait_3
	v_mov_b32_e32 v3, 1
	v_mov_b32_e32 v4, 0x2400
	global_atomic_add v4, v3, s[6:7]
	v_add_u32_e32 v4, 0x100, v4
	global_atomic_add v4, v3, s[6:7]
	v_add_u32_e32 v4, 0x100, v4
	global_atomic_add v4, v3, s[6:7]
	v_add_u32_e32 v4, 0x100, v4
	global_atomic_add v4, v3, s[6:7]
	v_add_u32_e32 v4, 0x100, v4
	global_atomic_add v4, v3, s[6:7]
	v_add_u32_e32 v4, 0x100, v4
	global_atomic_add v4, v3, s[6:7]
	v_add_u32_e32 v4, 0x100, v4
	global_atomic_add v4, v3, s[6:7]
	v_add_u32_e32 v4, 0x100, v4
	global_atomic_add v4, v3, s[6:7]
	v_add_u32_e32 v4, 0x100, v4
	global_atomic_add v4, v3, s[6:7]
	v_add_u32_e32 v4, 0x100, v4
	global_atomic_add v4, v3, s[6:7]
	v_add_u32_e32 v4, 0x100, v4
	global_atomic_add v4, v3, s[6:7]
	v_add_u32_e32 v4, 0x100, v4
	global_atomic_add v4, v3, s[6:7]
	v_add_u32_e32 v4, 0x100, v4
	global_atomic_add v4, v3, s[6:7]
	v_add_u32_e32 v4, 0x100, v4
	global_atomic_add v4, v3, s[6:7]
	v_add_u32_e32 v4, 0x100, v4
	global_atomic_add v4, v3, s[6:7]
	v_add_u32_e32 v4, 0x100, v4
	global_atomic_add v4, v3, s[6:7]
	v_add_u32_e32 v4, 0x100, v4
	v_mov_b32_e32 v4, 0x7f000
	global_atomic_add v4, v3, s[30:31] offset:1280
.Lxb_wait_3:
	v_mov_b32_e32 v4, 0x2000
	v_mov_b32_e32 v5, 0x200
	s_mov_b32 s17, 0
.Lxb_spin_3:
	global_load_dword v1, v4, s[8:9] offset:1024 sc1
	s_waitcnt vmcnt(0)
	v_readfirstlane_b32 s16, v1
	s_cmp_lg_u32 s16, s10
	s_cbranch_scc1 .Lxb_done_3
	s_sleep 1
	s_add_u32 s17, s17, 1
	s_and_b32 s16, s17, 0xff
	s_cmp_lg_u32 s16, 0
	s_cbranch_scc1 .Lxb_spin_3
	global_load_dword v1, v5, s[6:7] sc1
	s_waitcnt vmcnt(0)
	v_readfirstlane_b32 s16, v1
	s_cmp_lg_u32 s16, 0
	s_cbranch_scc1 .Lxb_done_3
	s_cmp_lt_u32 s17, 0x40000
	s_cbranch_scc1 .Lxb_spin_3
	v_mov_b32_e32 v3, 1
	global_atomic_add v5, v3, s[6:7]
	s_waitcnt vmcnt(0)

.LBB0_1602:
	v_readlane_b32 s66, v251, 55
	v_readlane_b32 s67, v251, 56
	s_cmp_gt_i32 s67, 4
	s_cbranch_scc0 .LBB0_1652
	s_waitcnt vmcnt(0)
	s_waitcnt vmcnt(63) expcnt(7) lgkmcnt(15)
	s_barrier
	s_mov_b64 s[4:5], exec
	v_readlane_b32 s2, v251, 3
	v_readlane_b32 s3, v251, 4
	s_and_b64 s[2:3], s[4:5], s[2:3]
	s_mov_b64 exec, s[2:3]
	s_cbranch_execz .Lxb_done_4
	v_mov_b32_e32 v0, 0
	s_waitcnt vmcnt(0) expcnt(0) lgkmcnt(0)
	ds_read_b32 v2, v0
	ds_read_b32 v1, v0 offset:4
	v_readlane_b32 s0, v251, 2
	v_readlane_b32 s6, v251, 5
	v_readlane_b32 s7, v251, 6
	s_lshl_b32 s0, s0, 8
	s_add_u32 s8, s6, s0
	s_addc_u32 s9, s7, 0
	v_mov_b32_e32 v3, 1
	v_mov_b32_e32 v4, 0x1000
	s_nop 4
	global_atomic_add v3, v4, v3, s[8:9] offset:1024 sc0
	buffer_inv sc1
	s_sub_u32 s10, 3, s66
	s_add_u32 s11, s10, 1
	s_waitcnt lgkmcnt(0)
	v_readfirstlane_b32 s12, v2
	v_readfirstlane_b32 s13, v1
	s_mul_i32 s14, s12, s11
	s_mul_i32 s15, s13, s11
	s_waitcnt vmcnt(0)
	v_readfirstlane_b32 s16, v3
	s_add_u32 s16, s16, 1
	s_cmp_lg_u32 s16, s14
	s_cbranch_scc1 .Lxb_wait_4
	buffer_wbl2 sc1
	s_waitcnt vmcnt(0)
	v_mov_b32_e32 v3, 1
	v_mov_b32_e32 v4, 0x7f000
	global_atomic_add v3, v4, v3, s[30:31] offset:1024 sc0
	s_waitcnt vmcnt(0)
	v_readfirstlane_b32 s16, v3
	s_add_u32 s16, s16, 1
	s_cmp_lg_u32 s16, s15
	s_cbranch_scc1 .Lxb_wait_4
	v_mov_b32_e32 v3, 1
	v_mov_b32_e32 v4, 0x2400
	global_atomic_add v4, v3, s[6:7]
	v_add_u32_e32 v4, 0x100, v4
	global_atomic_add v4, v3, s[6:7]
	v_add_u32_e32 v4, 0x100, v4
	global_atomic_add v4, v3, s[6:7]
	v_add_u32_e32 v4, 0x100, v4
	global_atomic_add v4, v3, s[6:7]
	v_add_u32_e32 v4, 0x100, v4
	global_atomic_add v4, v3, s[6:7]
	v_add_u32_e32 v4, 0x100, v4
	global_atomic_add v4, v3, s[6:7]
	v_add_u32_e32 v4, 0x100, v4
	global_atomic_add v4, v3, s[6:7]
	v_add_u32_e32 v4, 0x100, v4
	global_atomic_add v4, v3, s[6:7]
	v_add_u32_e32 v4, 0x100, v4
	global_atomic_add v4, v3, s[6:7]
	v_add_u32_e32 v4, 0x100, v4
	global_atomic_add v4, v3, s[6:7]
	v_add_u32_e32 v4, 0x100, v4
	global_atomic_add v4, v3, s[6:7]
	v_add_u32_e32 v4, 0x100, v4
	global_atomic_add v4, v3, s[6:7]
	v_add_u32_e32 v4, 0x100, v4
	global_atomic_add v4, v3, s[6:7]
	v_add_u32_e32 v4, 0x100, v4
	global_atomic_add v4, v3, s[6:7]
	v_add_u32_e32 v4, 0x100, v4
	global_atomic_add v4, v3, s[6:7]
	v_add_u32_e32 v4, 0x100, v4
	global_atomic_add v4, v3, s[6:7]
	v_add_u32_e32 v4, 0x100, v4
	v_mov_b32_e32 v4, 0x7f000
	global_atomic_add v4, v3, s[30:31] offset:1280

.Lxb_done_4:
	s_or_b64 exec, exec, s[4:5]
	s_waitcnt lgkmcnt(0)
	s_barrier
.LBB0_1652:
	s_cmp_gt_i32 s66, 4
	s_cselect_b64 s[0:1], -1, 0
	s_cmp_lt_i32 s67, 5
	s_cselect_b64 s[2:3], -1, 0
	s_or_b64 s[0:1], s[0:1], s[2:3]
	s_and_b64 vcc, exec, s[0:1]
	s_cbranch_vccnz .LBB0_1737
	s_lshr_b32 s3, s78, 3
	s_ashr_i32 s20, s64, 3
	v_readlane_b32 s36, v251, 23
	s_cmpk_gt_u32 s78, 0xff
	v_readlane_b32 s42, v251, 29
	v_readlane_b32 s43, v251, 30
	v_readlane_b32 s37, v251, 24
	v_readlane_b32 s38, v251, 25
	v_readlane_b32 s39, v251, 26
	v_readlane_b32 s40, v251, 27
	v_readlane_b32 s41, v251, 28
	v_readlane_b32 s44, v251, 31
	v_readlane_b32 s45, v251, 32
	v_readlane_b32 s46, v251, 33
	v_readlane_b32 s47, v251, 34
	v_readlane_b32 s48, v251, 35
	v_readlane_b32 s49, v251, 36
	v_readlane_b32 s50, v251, 37
	v_readlane_b32 s51, v251, 38
	s_cbranch_scc1 .LBB0_1662
	s_add_u32 s0, s30, 0xb793e00
	s_addc_u32 s1, s31, 0
	s_add_u32 s4, s30, 0x9393e00
	s_addc_u32 s5, s31, 0
	s_add_u32 s6, s30, 0x9b93e00
	s_addc_u32 s7, s31, 0
	s_add_u32 s8, s30, 0x1993e00
	s_addc_u32 s9, s31, 0
	s_add_u32 s10, s30, 0xa393e00
	s_addc_u32 s11, s31, 0
	s_lshl_b32 s2, s78, 10
	s_and_b32 s21, s2, 0x1c00
	s_lshl_b32 s22, s3, 7
	s_lshl_b32 s23, s20, 7
	s_lshl_b32 s24, s3, 4
	s_lshl_b32 s25, s20, 4
	s_add_u32 s14, s42, 0x100
	s_mov_b64 s[12:13], 0x100
	s_addc_u32 s15, s43, 0
	v_mov_b32_e32 v137, 0
	s_mov_b32 s26, 0x8000
	s_mov_b32 s27, 0x10000
	s_mov_b32 s33, 0x18000
	s_movk_i32 s34, 0x90
	s_mov_b32 s35, 0xfffffc0
	s_mov_b32 s40, s3
	s_branch .LBB0_1656

.LBB0_1687:
	s_cmp_gt_i32 s67, 5
	s_cbranch_scc0 .LBB0_1737
	s_waitcnt vmcnt(0)
	s_waitcnt vmcnt(63) expcnt(7) lgkmcnt(15)
	s_barrier
	s_mov_b64 s[4:5], exec
	v_readlane_b32 s2, v251, 3
	v_readlane_b32 s3, v251, 4
	s_and_b64 s[2:3], s[4:5], s[2:3]
	s_mov_b64 exec, s[2:3]
	s_cbranch_execz .Lxb_done_5
	v_mov_b32_e32 v0, 0
	s_waitcnt vmcnt(0) expcnt(0) lgkmcnt(0)
	ds_read_b32 v2, v0
	ds_read_b32 v1, v0 offset:4
	v_readlane_b32 s0, v251, 2
	v_readlane_b32 s6, v251, 5
	v_readlane_b32 s7, v251, 6
	s_lshl_b32 s0, s0, 8
	s_add_u32 s8, s6, s0
	s_addc_u32 s9, s7, 0
	v_mov_b32_e32 v3, 1
	v_mov_b32_e32 v4, 0x1000
	s_nop 4
	global_atomic_add v3, v4, v3, s[8:9] offset:1024 sc0
	buffer_inv sc1
	s_sub_u32 s10, 4, s66
	s_add_u32 s11, s10, 1
	s_waitcnt lgkmcnt(0)
	v_readfirstlane_b32 s12, v2
	v_readfirstlane_b32 s13, v1
	s_mul_i32 s14, s12, s11
	s_mul_i32 s15, s13, s11
	s_waitcnt vmcnt(0)
	v_readfirstlane_b32 s16, v3
	s_add_u32 s16, s16, 1
	s_cmp_lg_u32 s16, s14
	s_cbranch_scc1 .Lxb_wait_5
	buffer_wbl2 sc1
	s_waitcnt vmcnt(0)
	v_mov_b32_e32 v3, 1
	v_mov_b32_e32 v4, 0x7f000
	global_atomic_add v3, v4, v3, s[30:31] offset:1024 sc0
	s_waitcnt vmcnt(0)
	v_readfirstlane_b32 s16, v3
	s_add_u32 s16, s16, 1
	s_cmp_lg_u32 s16, s15
	s_cbranch_scc1 .Lxb_wait_5
	v_mov_b32_e32 v3, 1
	v_mov_b32_e32 v4, 0x2400
	global_atomic_add v4, v3, s[6:7]
	v_add_u32_e32 v4, 0x100, v4
	global_atomic_add v4, v3, s[6:7]
	v_add_u32_e32 v4, 0x100, v4
	global_atomic_add v4, v3, s[6:7]
	v_add_u32_e32 v4, 0x100, v4
	global_atomic_add v4, v3, s[6:7]
	v_add_u32_e32 v4, 0x100, v4
	global_atomic_add v4, v3, s[6:7]
	v_add_u32_e32 v4, 0x100, v4
	global_atomic_add v4, v3, s[6:7]
	v_add_u32_e32 v4, 0x100, v4
	global_atomic_add v4, v3, s[6:7]
	v_add_u32_e32 v4, 0x100, v4
	global_atomic_add v4, v3, s[6:7]
	v_add_u32_e32 v4, 0x100, v4
	global_atomic_add v4, v3, s[6:7]
	v_add_u32_e32 v4, 0x100, v4
	global_atomic_add v4, v3, s[6:7]
	v_add_u32_e32 v4, 0x100, v4
	global_atomic_add v4, v3, s[6:7]
	v_add_u32_e32 v4, 0x100, v4
	global_atomic_add v4, v3, s[6:7]
	v_add_u32_e32 v4, 0x100, v4
	global_atomic_add v4, v3, s[6:7]
	v_add_u32_e32 v4, 0x100, v4
	global_atomic_add v4, v3, s[6:7]
	v_add_u32_e32 v4, 0x100, v4
	global_atomic_add v4, v3, s[6:7]
	v_add_u32_e32 v4, 0x100, v4
	global_atomic_add v4, v3, s[6:7]
	v_add_u32_e32 v4, 0x100, v4
	v_mov_b32_e32 v4, 0x7f000
	global_atomic_add v4, v3, s[30:31] offset:1280

.Lxb_done_5:
	s_or_b64 exec, exec, s[4:5]
	s_waitcnt lgkmcnt(0)
	s_barrier
.LBB0_1737:
	s_cmp_gt_i32 s66, 5
	s_cselect_b64 s[0:1], -1, 0
	s_cmp_lt_i32 s67, 6
	s_cselect_b64 s[2:3], -1, 0
	s_or_b64 s[0:1], s[0:1], s[2:3]
	s_and_b64 vcc, exec, s[0:1]
	s_cbranch_vccnz .LBB0_1812
	s_cmpk_gt_u32 s78, 0x1ff
	s_cbranch_scc1 .LBB0_1762
	s_lshl_b32 s0, s78, 3
	s_ashr_i32 s2, s64, 3
	s_and_b32 s3, s0, 56
	s_add_u32 s33, s30, 0x1a13e00
	s_addc_u32 s52, s31, 0
	s_add_u32 s4, s30, 0x5393e00
	s_addc_u32 s5, s31, 0
	s_add_u32 s53, s30, 0x9393e00
	s_addc_u32 s54, s31, 0
	s_lshr_b32 s55, s78, 3
	s_add_u32 s6, s30, 0x1a2bf80
	s_addc_u32 s7, s31, 0
	s_lshl_b32 s56, s55, 4
	s_lshl_b32 s57, s2, 4
	s_add_u32 s8, s30, 0x1a23f00
	s_addc_u32 s9, s31, 0
	s_add_u32 s10, s30, 0x1a1bf80
	s_addc_u32 s11, s31, 0
	s_add_u32 s12, s30, 0x1a1bf00
	s_addc_u32 s13, s31, 0
	s_and_b32 s0, s78, 7
	s_lshl_b32 s58, s0, 10
	s_add_u32 s14, s30, 0x1a13f00
	s_addc_u32 s15, s31, 0
	s_mov_b32 s59, 0xfffffc0
	s_movk_i32 s60, 0x110
	s_mov_b32 s17, 0
	v_mov_b32_e32 v129, 0
	s_mov_b32 s61, 0x8000
	s_mov_b32 s62, 0x10000
	s_mov_b32 s63, 0x18000
	s_movk_i32 s65, 0x90
	s_mov_b64 s[18:19], 0x100
	s_movk_i32 s66, 0x1800
	s_mov_b32 s67, s55
	s_branch .LBB0_1741

.LBB0_1762:
	v_readlane_b32 s66, v251, 55
	v_readlane_b32 s67, v251, 56
	s_cmp_gt_i32 s67, 6
	s_cbranch_scc0 .LBB0_1812
	s_waitcnt vmcnt(0)
	s_waitcnt vmcnt(63) expcnt(7) lgkmcnt(15)
	s_barrier
	s_mov_b64 s[4:5], exec
	v_readlane_b32 s2, v251, 3
	v_readlane_b32 s3, v251, 4
	s_and_b64 s[2:3], s[4:5], s[2:3]
	s_mov_b64 exec, s[2:3]
	s_cbranch_execz .Lxb_done_6
	v_mov_b32_e32 v0, 0
	s_waitcnt vmcnt(0) expcnt(0) lgkmcnt(0)
	ds_read_b32 v2, v0
	ds_read_b32 v1, v0 offset:4
	v_readlane_b32 s0, v251, 2
	v_readlane_b32 s6, v251, 5
	v_readlane_b32 s7, v251, 6
	s_lshl_b32 s0, s0, 8
	s_add_u32 s8, s6, s0
	s_addc_u32 s9, s7, 0
	v_mov_b32_e32 v3, 1
	v_mov_b32_e32 v4, 0x1000
	s_nop 4
	global_atomic_add v3, v4, v3, s[8:9] offset:1024 sc0
	buffer_inv sc1
	s_sub_u32 s10, 5, s66
	s_add_u32 s11, s10, 1
	s_waitcnt lgkmcnt(0)
	v_readfirstlane_b32 s12, v2
	v_readfirstlane_b32 s13, v1
	s_mul_i32 s14, s12, s11
	s_mul_i32 s15, s13, s11
	s_waitcnt vmcnt(0)
	v_readfirstlane_b32 s16, v3
	s_add_u32 s16, s16, 1
	s_cmp_lg_u32 s16, s14
	s_cbranch_scc1 .Lxb_wait_6
	buffer_wbl2 sc1
	s_waitcnt vmcnt(0)
	v_mov_b32_e32 v3, 1
	v_mov_b32_e32 v4, 0x7f000
	global_atomic_add v3, v4, v3, s[30:31] offset:1024 sc0
	s_waitcnt vmcnt(0)
	v_readfirstlane_b32 s16, v3
	s_add_u32 s16, s16, 1
	s_cmp_lg_u32 s16, s15
	s_cbranch_scc1 .Lxb_wait_6
	v_mov_b32_e32 v3, 1
	v_mov_b32_e32 v4, 0x2400
	global_atomic_add v4, v3, s[6:7]
	v_add_u32_e32 v4, 0x100, v4
	global_atomic_add v4, v3, s[6:7]
	v_add_u32_e32 v4, 0x100, v4
	global_atomic_add v4, v3, s[6:7]
	v_add_u32_e32 v4, 0x100, v4
	global_atomic_add v4, v3, s[6:7]
	v_add_u32_e32 v4, 0x100, v4
	global_atomic_add v4, v3, s[6:7]
	v_add_u32_e32 v4, 0x100, v4
	global_atomic_add v4, v3, s[6:7]
	v_add_u32_e32 v4, 0x100, v4
	global_atomic_add v4, v3, s[6:7]
	v_add_u32_e32 v4, 0x100, v4
	global_atomic_add v4, v3, s[6:7]
	v_add_u32_e32 v4, 0x100, v4
	global_atomic_add v4, v3, s[6:7]
	v_add_u32_e32 v4, 0x100, v4
	global_atomic_add v4, v3, s[6:7]
	v_add_u32_e32 v4, 0x100, v4
	global_atomic_add v4, v3, s[6:7]
	v_add_u32_e32 v4, 0x100, v4
	global_atomic_add v4, v3, s[6:7]
	v_add_u32_e32 v4, 0x100, v4
	global_atomic_add v4, v3, s[6:7]
	v_add_u32_e32 v4, 0x100, v4
	global_atomic_add v4, v3, s[6:7]
	v_add_u32_e32 v4, 0x100, v4
	global_atomic_add v4, v3, s[6:7]
	v_add_u32_e32 v4, 0x100, v4
	global_atomic_add v4, v3, s[6:7]
	v_add_u32_e32 v4, 0x100, v4
	v_mov_b32_e32 v4, 0x7f000
	global_atomic_add v4, v3, s[30:31] offset:1280

.Lxb_done_6:
	s_or_b64 exec, exec, s[4:5]
	s_waitcnt lgkmcnt(0)
	s_barrier
.LBB0_1812:
	s_cmp_gt_i32 s66, 6
	s_cselect_b64 s[0:1], -1, 0
	s_cmp_lt_i32 s67, 7
	s_cselect_b64 s[2:3], -1, 0
	s_or_b64 s[0:1], s[0:1], s[2:3]
	s_and_b64 vcc, exec, s[0:1]
	s_cbranch_vccnz .LBB0_1878
	s_cmpk_gt_u32 s78, 0x1ff
	s_cbranch_scc1 .LBB0_1828
	s_lshl_b32 s0, s78, 3
	s_ashr_i32 s2, s64, 3
	s_and_b32 s3, s0, 56
	s_add_u32 s4, s30, 0x9393e00
	s_addc_u32 s5, s31, 0
	s_add_u32 s6, s30, 0x1d13e00
	s_addc_u32 s7, s31, 0
	s_cmp_lt_u32 s3, 32
	s_cselect_b64 s[8:9], -1, 0
	s_lshl_b32 s0, s78, 10
	s_lshr_b32 s17, s78, 3
	s_and_b32 s26, s0, 0x1c00
	v_mbcnt_lo_u32_b32 v0, -1, 0
	s_lshl_b32 s24, s17, 4
	s_lshl_b32 s25, s2, 4
	s_or_b32 s27, s26, 24
	s_or_b32 s33, s26, 16
	s_or_b32 s34, s26, 8
	v_mov_b32_e32 v97, 0
	s_mov_b32 s35, 0x10000
	s_mov_b32 s11, 0
	s_mov_b32 s40, 0x20000
	s_mov_b32 s41, 0x30000
	s_movk_i32 s44, 0x90
	s_mov_b32 s45, 0xfffffc0
	s_mov_b32 s46, 0x9393000
	s_mov_b32 s47, 0x93a3000
	s_mov_b32 s48, 0x93b3000
	s_mov_b32 s49, 0x93c3000
	s_mov_b32 s50, 0x1d13000
	s_mov_b32 s51, 0x1d23000
	s_mov_b32 s52, 0x1d33000
	s_mov_b32 s53, 0x1d43000
	s_mov_b64 s[12:13], 0x100
	s_mov_b64 s[14:15], 0x2000
	s_movk_i32 s54, 0x2000
	s_movk_i32 s55, 0x210
	s_mov_b32 s16, 0x3fb504f3
	s_mov_b32 s56, 0xd793000
	v_mbcnt_hi_u32_b32 v102, -1, v0
	s_mov_b32 s57, s17
	s_branch .LBB0_1816

.LBB0_1828:
	s_cmp_gt_i32 s67, 7
	s_cbranch_scc0 .LBB0_1878
	s_waitcnt vmcnt(0)
	s_waitcnt vmcnt(63) expcnt(7) lgkmcnt(15)
	s_barrier
	s_mov_b64 s[4:5], exec
	v_readlane_b32 s2, v251, 3
	v_readlane_b32 s3, v251, 4
	s_and_b64 s[2:3], s[4:5], s[2:3]
	s_mov_b64 exec, s[2:3]
	s_cbranch_execz .Lxb_done_7
	v_mov_b32_e32 v0, 0
	s_waitcnt vmcnt(0) expcnt(0) lgkmcnt(0)
	ds_read_b32 v2, v0
	ds_read_b32 v1, v0 offset:4
	v_readlane_b32 s0, v251, 2
	v_readlane_b32 s6, v251, 5
	v_readlane_b32 s7, v251, 6
	s_lshl_b32 s0, s0, 8
	s_add_u32 s8, s6, s0
	s_addc_u32 s9, s7, 0
	v_mov_b32_e32 v3, 1
	v_mov_b32_e32 v4, 0x1000
	s_nop 4
	global_atomic_add v3, v4, v3, s[8:9] offset:1024 sc0
	buffer_inv sc1
	s_sub_u32 s10, 6, s66
	s_add_u32 s11, s10, 1
	s_waitcnt lgkmcnt(0)
	v_readfirstlane_b32 s12, v2
	v_readfirstlane_b32 s13, v1
	s_mul_i32 s14, s12, s11
	s_mul_i32 s15, s13, s11
	s_waitcnt vmcnt(0)
	v_readfirstlane_b32 s16, v3
	s_add_u32 s16, s16, 1
	s_cmp_lg_u32 s16, s14
	s_cbranch_scc1 .Lxb_wait_7
	buffer_wbl2 sc1
	s_waitcnt vmcnt(0)
	v_mov_b32_e32 v3, 1
	v_mov_b32_e32 v4, 0x7f000
	global_atomic_add v3, v4, v3, s[30:31] offset:1024 sc0
	s_waitcnt vmcnt(0)
	v_readfirstlane_b32 s16, v3
	s_add_u32 s16, s16, 1
	s_cmp_lg_u32 s16, s15
	s_cbranch_scc1 .Lxb_wait_7
	v_mov_b32_e32 v3, 1
	v_mov_b32_e32 v4, 0x2400
	global_atomic_add v4, v3, s[6:7]
	v_add_u32_e32 v4, 0x100, v4
	global_atomic_add v4, v3, s[6:7]
	v_add_u32_e32 v4, 0x100, v4
	global_atomic_add v4, v3, s[6:7]
	v_add_u32_e32 v4, 0x100, v4
	global_atomic_add v4, v3, s[6:7]
	v_add_u32_e32 v4, 0x100, v4
	global_atomic_add v4, v3, s[6:7]
	v_add_u32_e32 v4, 0x100, v4
	global_atomic_add v4, v3, s[6:7]
	v_add_u32_e32 v4, 0x100, v4
	global_atomic_add v4, v3, s[6:7]
	v_add_u32_e32 v4, 0x100, v4
	global_atomic_add v4, v3, s[6:7]
	v_add_u32_e32 v4, 0x100, v4
	global_atomic_add v4, v3, s[6:7]
	v_add_u32_e32 v4, 0x100, v4
	global_atomic_add v4, v3, s[6:7]
	v_add_u32_e32 v4, 0x100, v4
	global_atomic_add v4, v3, s[6:7]
	v_add_u32_e32 v4, 0x100, v4
	global_atomic_add v4, v3, s[6:7]
	v_add_u32_e32 v4, 0x100, v4
	global_atomic_add v4, v3, s[6:7]
	v_add_u32_e32 v4, 0x100, v4
	global_atomic_add v4, v3, s[6:7]
	v_add_u32_e32 v4, 0x100, v4
	global_atomic_add v4, v3, s[6:7]
	v_add_u32_e32 v4, 0x100, v4
	global_atomic_add v4, v3, s[6:7]
	v_add_u32_e32 v4, 0x100, v4
	v_mov_b32_e32 v4, 0x7f000
	global_atomic_add v4, v3, s[30:31] offset:1280

.Lxb_done_7:
	s_or_b64 exec, exec, s[4:5]
	s_waitcnt lgkmcnt(0)
	s_barrier
.LBB0_1878:
	s_cmp_gt_i32 s66, 7
	s_cselect_b64 s[0:1], -1, 0
	s_cmp_lt_i32 s67, 8
	s_cselect_b64 s[2:3], -1, 0
	s_or_b64 s[0:1], s[0:1], s[2:3]
	s_and_b64 vcc, exec, s[0:1]
	s_cbranch_vccnz .LBB0_1932
	v_readlane_b32 s36, v250, 6
	s_cmpk_gt_i32 s78, 0x3ff
	v_readlane_b32 s37, v250, 7
	v_readlane_b32 s38, v250, 8
	v_readlane_b32 s39, v250, 9
	v_readlane_b32 s40, v250, 10
	v_readlane_b32 s41, v250, 11
	v_readlane_b32 s42, v250, 12
	v_readlane_b32 s43, v250, 13
	v_readlane_b32 s44, v250, 14
	v_readlane_b32 s45, v250, 15
	v_readlane_b32 s46, v250, 16
	v_readlane_b32 s47, v250, 17
	v_readlane_b32 s48, v250, 18
	v_readlane_b32 s49, v250, 19
	v_readlane_b32 s50, v250, 20
	v_readlane_b32 s51, v250, 21
	s_cbranch_scc1 .LBB0_1882
	s_add_u32 s2, s30, 0x3c000
	s_addc_u32 s3, s31, 0
	s_add_u32 s0, s30, 0xab93e00
	s_addc_u32 s1, s31, 0
	s_add_u32 s11, s30, 0xd793e00
	s_addc_u32 s14, s31, 0
	s_lshl_b32 s4, s78, 4
	s_lshl_b32 s5, s78, 3
	s_or_b32 s4, s4, 14
	s_lshl_b32 s15, s64, 4
	s_or_b32 s6, s5, 7
	s_lshl_b32 s16, s64, 3
	s_mov_b32 s9, 0
	s_waitcnt vmcnt(11)
	v_mov_b32_e32 v12, 0
	s_mov_b32 s10, 0x3a800000
	s_mov_b32 s17, 0x800000
	s_movk_i32 s18, 0x4000
	s_movk_i32 s19, 0x3000
	s_mov_b32 s20, s78

.LBB0_1942:
	s_cmp_gt_i32 s67, 9
	s_cbranch_scc0 .LBB0_1992
	s_waitcnt vmcnt(0)
	s_waitcnt vmcnt(63) expcnt(7) lgkmcnt(15)
	s_barrier
	s_mov_b64 s[4:5], exec
	v_readlane_b32 s2, v251, 3
	v_readlane_b32 s3, v251, 4
	s_and_b64 s[2:3], s[4:5], s[2:3]
	s_mov_b64 exec, s[2:3]
	s_cbranch_execz .Lxb_done_9
	v_mov_b32_e32 v0, 0
	s_waitcnt vmcnt(0) expcnt(0) lgkmcnt(0)
	ds_read_b32 v2, v0
	ds_read_b32 v1, v0 offset:4
	v_readlane_b32 s0, v251, 2
	v_readlane_b32 s6, v251, 5
	v_readlane_b32 s7, v251, 6
	s_lshl_b32 s0, s0, 8
	s_add_u32 s8, s6, s0
	s_addc_u32 s9, s7, 0
	v_mov_b32_e32 v3, 1
	v_mov_b32_e32 v4, 0x1000
	s_nop 4
	global_atomic_add v3, v4, v3, s[8:9] offset:1024 sc0
	buffer_inv sc1
	s_sub_u32 s10, 8, s66
	s_add_u32 s11, s10, 1
	s_waitcnt lgkmcnt(0)
	v_readfirstlane_b32 s12, v2
	v_readfirstlane_b32 s13, v1
	s_mul_i32 s14, s12, s11
	s_mul_i32 s15, s13, s11
	s_waitcnt vmcnt(0)
	v_readfirstlane_b32 s16, v3
	s_add_u32 s16, s16, 1
	s_cmp_lg_u32 s16, s14
	s_cbranch_scc1 .Lxb_wait_9
	buffer_wbl2 sc1
	s_waitcnt vmcnt(0)
	v_mov_b32_e32 v3, 1
	v_mov_b32_e32 v4, 0x7f000
	global_atomic_add v3, v4, v3, s[30:31] offset:1024 sc0
	s_waitcnt vmcnt(0)
	v_readfirstlane_b32 s16, v3
	s_add_u32 s16, s16, 1
	s_cmp_lg_u32 s16, s15
	s_cbranch_scc1 .Lxb_wait_9
	v_mov_b32_e32 v3, 1
	v_mov_b32_e32 v4, 0x2400
	global_atomic_add v4, v3, s[6:7]
	v_add_u32_e32 v4, 0x100, v4
	global_atomic_add v4, v3, s[6:7]
	v_add_u32_e32 v4, 0x100, v4
	global_atomic_add v4, v3, s[6:7]
	v_add_u32_e32 v4, 0x100, v4
	global_atomic_add v4, v3, s[6:7]
	v_add_u32_e32 v4, 0x100, v4
	global_atomic_add v4, v3, s[6:7]
	v_add_u32_e32 v4, 0x100, v4
	global_atomic_add v4, v3, s[6:7]
	v_add_u32_e32 v4, 0x100, v4
	global_atomic_add v4, v3, s[6:7]
	v_add_u32_e32 v4, 0x100, v4
	global_atomic_add v4, v3, s[6:7]
	v_add_u32_e32 v4, 0x100, v4
	global_atomic_add v4, v3, s[6:7]
	v_add_u32_e32 v4, 0x100, v4
	global_atomic_add v4, v3, s[6:7]
	v_add_u32_e32 v4, 0x100, v4
	global_atomic_add v4, v3, s[6:7]
	v_add_u32_e32 v4, 0x100, v4
	global_atomic_add v4, v3, s[6:7]
	v_add_u32_e32 v4, 0x100, v4
	global_atomic_add v4, v3, s[6:7]
	v_add_u32_e32 v4, 0x100, v4
	global_atomic_add v4, v3, s[6:7]
	v_add_u32_e32 v4, 0x100, v4
	global_atomic_add v4, v3, s[6:7]
	v_add_u32_e32 v4, 0x100, v4
	global_atomic_add v4, v3, s[6:7]
	v_add_u32_e32 v4, 0x100, v4
	v_mov_b32_e32 v4, 0x7f000
	global_atomic_add v4, v3, s[30:31] offset:1280

.Lxb_done_9:
	s_or_b64 exec, exec, s[4:5]
	s_waitcnt lgkmcnt(0)
	s_barrier
.LBB0_1992:
	s_cmp_gt_i32 s66, 9
	s_cselect_b64 s[0:1], -1, 0
	s_cmp_lt_i32 s67, 10
	s_cselect_b64 s[2:3], -1, 0
	s_or_b64 s[0:1], s[0:1], s[2:3]
	s_and_b64 vcc, exec, s[0:1]
	s_cbranch_vccnz .LBB0_2057
	s_cmpk_gt_i32 s78, 0x1ff
	s_cbranch_scc1 .LBB0_2007
	v_readlane_b32 s4, v250, 6
	v_readlane_b32 s10, v250, 12
	v_readlane_b32 s11, v250, 13
	s_add_u32 s0, s10, 0x2c00
	s_addc_u32 s1, s11, 0
	v_readlane_b32 s5, v250, 7
	s_add_u32 s4, s10, 0x5800
	v_readlane_b32 s6, v250, 8
	s_addc_u32 s5, s11, 0
	v_readlane_b32 s7, v250, 9
	s_add_u32 s6, s10, 0x8400
	v_readlane_b32 s8, v250, 10
	s_addc_u32 s7, s11, 0
	v_readlane_b32 s9, v250, 11
	s_add_u32 s8, s10, 0xb000
	s_addc_u32 s9, s11, 0
	s_add_u32 s10, s10, 0xdc00
	v_readlane_b32 s12, v250, 14
	s_addc_u32 s11, s11, 0
	v_readlane_b32 s13, v250, 15
	s_add_u32 s12, s12, 0x2c00
	s_addc_u32 s13, s13, 0
	s_add_u32 s2, s30, 0x5393e00
	s_addc_u32 s3, s31, 0
	s_lshl_b32 s20, s78, 4
	s_lshl_b32 s21, s64, 4
	s_movk_i32 s22, 0xb0
	s_movk_i32 s23, 0xe0
	s_movk_i32 s24, 0xff
	s_mov_b32 s25, 0xab95000
	v_mov_b32_e32 v0, 0
	s_mov_b32 s26, s78
	v_readlane_b32 s14, v250, 16
	v_readlane_b32 s15, v250, 17
	v_readlane_b32 s16, v250, 18
	v_readlane_b32 s17, v250, 19
	v_readlane_b32 s18, v250, 20
	v_readlane_b32 s19, v250, 21
	s_branch .LBB0_1996

.LBB0_2007:
	s_cmp_gt_i32 s67, 10
	s_cbranch_scc0 .LBB0_2057
	s_waitcnt vmcnt(0)
	s_waitcnt vmcnt(63) expcnt(7) lgkmcnt(15)
	s_barrier
	s_mov_b64 s[4:5], exec
	v_readlane_b32 s2, v251, 3
	v_readlane_b32 s3, v251, 4
	s_and_b64 s[2:3], s[4:5], s[2:3]
	s_mov_b64 exec, s[2:3]
	s_cbranch_execz .Lxb_done_10
	v_mov_b32_e32 v0, 0
	s_waitcnt vmcnt(0) expcnt(0) lgkmcnt(0)
	ds_read_b32 v2, v0
	ds_read_b32 v1, v0 offset:4
	v_readlane_b32 s0, v251, 2
	v_readlane_b32 s6, v251, 5
	v_readlane_b32 s7, v251, 6
	s_lshl_b32 s0, s0, 8
	s_add_u32 s8, s6, s0
	s_addc_u32 s9, s7, 0
	v_mov_b32_e32 v3, 1
	v_mov_b32_e32 v4, 0x1000
	s_nop 4
	global_atomic_add v3, v4, v3, s[8:9] offset:1024 sc0
	buffer_inv sc1
	s_sub_u32 s10, 9, s66
	s_add_u32 s11, s10, 1
	s_waitcnt lgkmcnt(0)
	v_readfirstlane_b32 s12, v2
	v_readfirstlane_b32 s13, v1
	s_mul_i32 s14, s12, s11
	s_mul_i32 s15, s13, s11
	s_waitcnt vmcnt(0)
	v_readfirstlane_b32 s16, v3
	s_add_u32 s16, s16, 1
	s_cmp_lg_u32 s16, s14
	s_cbranch_scc1 .Lxb_wait_10
	buffer_wbl2 sc1
	s_waitcnt vmcnt(0)
	v_mov_b32_e32 v3, 1
	v_mov_b32_e32 v4, 0x7f000
	global_atomic_add v3, v4, v3, s[30:31] offset:1024 sc0
	s_waitcnt vmcnt(0)
	v_readfirstlane_b32 s16, v3
	s_add_u32 s16, s16, 1
	s_cmp_lg_u32 s16, s15
	s_cbranch_scc1 .Lxb_wait_10
	v_mov_b32_e32 v3, 1
	v_mov_b32_e32 v4, 0x2400
	global_atomic_add v4, v3, s[6:7]
	v_add_u32_e32 v4, 0x100, v4
	global_atomic_add v4, v3, s[6:7]
	v_add_u32_e32 v4, 0x100, v4
	global_atomic_add v4, v3, s[6:7]
	v_add_u32_e32 v4, 0x100, v4
	global_atomic_add v4, v3, s[6:7]
	v_add_u32_e32 v4, 0x100, v4
	global_atomic_add v4, v3, s[6:7]
	v_add_u32_e32 v4, 0x100, v4
	global_atomic_add v4, v3, s[6:7]
	v_add_u32_e32 v4, 0x100, v4
	global_atomic_add v4, v3, s[6:7]
	v_add_u32_e32 v4, 0x100, v4
	global_atomic_add v4, v3, s[6:7]
	v_add_u32_e32 v4, 0x100, v4
	global_atomic_add v4, v3, s[6:7]
	v_add_u32_e32 v4, 0x100, v4
	global_atomic_add v4, v3, s[6:7]
	v_add_u32_e32 v4, 0x100, v4
	global_atomic_add v4, v3, s[6:7]
	v_add_u32_e32 v4, 0x100, v4
	global_atomic_add v4, v3, s[6:7]
	v_add_u32_e32 v4, 0x100, v4
	global_atomic_add v4, v3, s[6:7]
	v_add_u32_e32 v4, 0x100, v4
	global_atomic_add v4, v3, s[6:7]
	v_add_u32_e32 v4, 0x100, v4
	global_atomic_add v4, v3, s[6:7]
	v_add_u32_e32 v4, 0x100, v4
	global_atomic_add v4, v3, s[6:7]
	v_add_u32_e32 v4, 0x100, v4
	v_mov_b32_e32 v4, 0x7f000
	global_atomic_add v4, v3, s[30:31] offset:1280

.Lxb_done_10:
	s_or_b64 exec, exec, s[4:5]
	s_waitcnt lgkmcnt(0)
	s_barrier
.LBB0_2057:
	s_cmp_gt_i32 s66, 10
	s_cselect_b64 s[0:1], -1, 0
	s_cmp_lt_i32 s67, 11
	s_cselect_b64 s[2:3], -1, 0
	s_or_b64 s[0:1], s[0:1], s[2:3]
	s_and_b64 vcc, exec, s[0:1]
	s_cbranch_vccnz .LBB0_2123
	s_cmpk_gt_u32 s78, 0x1ff
	s_cbranch_scc1 .LBB0_2073
	s_lshl_b32 s0, s78, 3
	s_ashr_i32 s2, s64, 3
	s_and_b32 s3, s0, 56
	s_add_u32 s0, s30, 0xab93e00
	s_addc_u32 s1, s31, 0
	s_add_u32 s8, s30, 0x2a13e00
	s_addc_u32 s9, s31, 0
	s_cmp_lt_u32 s3, 32
	s_cselect_b64 s[4:5], -1, 0
	s_add_u32 s15, s30, 0xd793e00
	s_addc_u32 s17, s31, 0
	s_add_u32 s24, s30, 0xe793e00
	s_addc_u32 s25, s31, 0
	s_lshl_b32 s6, s78, 10
	s_lshr_b32 s26, s78, 3
	s_and_b32 s34, s6, 0x1c00
	s_lshl_b32 s27, s26, 4
	s_lshl_b32 s33, s2, 4
	s_or_b32 s35, s34, 24
	s_or_b32 s36, s34, 16
	s_or_b32 s37, s34, 8
	s_add_u32 s6, s28, 8
	v_mbcnt_lo_u32_b32 v0, -1, 0
	s_addc_u32 s7, s29, 0
	s_movk_i32 s38, 0x1600
	v_mov_b64_e32 v[96:97], s[0:1]
	v_mov_b32_e32 v99, 0
	v_mov_b64_e32 v[100:101], s[8:9]
	s_mov_b32 s39, 0x2c000
	s_mov_b32 s9, 0
	s_mov_b32 s40, 0x58000
	s_mov_b32 s41, 0x84000
	s_movk_i32 s44, 0x90
	s_mov_b32 s45, 0xfffffc0
	v_mov_b64_e32 v[102:103], s[30:31]
	s_mov_b32 s46, 0xac17000
	s_mov_b32 s47, 0x2a13000
	s_mov_b32 s48, 0x2a3f000
	s_mov_b32 s49, 0x2a6b000
	s_mov_b32 s50, 0x2a97000
	s_mov_b64 s[10:11], 0x100
	s_mov_b64 s[12:13], 0x5000
	s_movk_i32 s51, 0x5000
	s_movk_i32 s52, 0x210
	s_mov_b32 s14, 0x3a800000
	s_mov_b32 s53, 0x800000
	s_mov_b32 s16, 0x3fb504f3
	s_mov_b32 s54, 0x8000
	s_mov_b32 s55, 0x10000
	s_mov_b32 s56, 0x18000
	s_mov_b64 s[18:19], 0x20000
	v_mbcnt_hi_u32_b32 v108, -1, v0
	s_mov_b32 s57, s26
	s_branch .LBB0_2061

.LBB0_2073:
	s_cmp_gt_i32 s67, 11
	s_cbranch_scc0 .LBB0_2123
	s_waitcnt vmcnt(0)
	s_waitcnt vmcnt(63) expcnt(7) lgkmcnt(15)
	s_barrier
	s_mov_b64 s[4:5], exec
	v_readlane_b32 s2, v251, 3
	v_readlane_b32 s3, v251, 4
	s_and_b64 s[2:3], s[4:5], s[2:3]
	s_mov_b64 exec, s[2:3]
	s_cbranch_execz .Lxb_done_11
	v_mov_b32_e32 v0, 0
	s_waitcnt vmcnt(0) expcnt(0) lgkmcnt(0)
	ds_read_b32 v2, v0
	ds_read_b32 v1, v0 offset:4
	v_readlane_b32 s0, v251, 2
	v_readlane_b32 s6, v251, 5
	v_readlane_b32 s7, v251, 6
	s_lshl_b32 s0, s0, 8
	s_add_u32 s8, s6, s0
	s_addc_u32 s9, s7, 0
	v_mov_b32_e32 v3, 1
	v_mov_b32_e32 v4, 0x1000
	s_nop 4
	global_atomic_add v3, v4, v3, s[8:9] offset:1024 sc0
	buffer_inv sc1
	s_sub_u32 s10, 10, s66
	s_add_u32 s11, s10, 1
	s_waitcnt lgkmcnt(0)
	v_readfirstlane_b32 s12, v2
	v_readfirstlane_b32 s13, v1
	s_mul_i32 s14, s12, s11
	s_mul_i32 s15, s13, s11
	s_waitcnt vmcnt(0)
	v_readfirstlane_b32 s16, v3
	s_add_u32 s16, s16, 1
	s_cmp_lg_u32 s16, s14
	s_cbranch_scc1 .Lxb_wait_11
	buffer_wbl2 sc1
	s_waitcnt vmcnt(0)
	v_mov_b32_e32 v3, 1
	v_mov_b32_e32 v4, 0x7f000
	global_atomic_add v3, v4, v3, s[30:31] offset:1024 sc0
	s_waitcnt vmcnt(0)
	v_readfirstlane_b32 s16, v3
	s_add_u32 s16, s16, 1
	s_cmp_lg_u32 s16, s15
	s_cbranch_scc1 .Lxb_wait_11
	v_mov_b32_e32 v3, 1
	v_mov_b32_e32 v4, 0x2400
	global_atomic_add v4, v3, s[6:7]
	v_add_u32_e32 v4, 0x100, v4
	global_atomic_add v4, v3, s[6:7]
	v_add_u32_e32 v4, 0x100, v4
	global_atomic_add v4, v3, s[6:7]
	v_add_u32_e32 v4, 0x100, v4
	global_atomic_add v4, v3, s[6:7]
	v_add_u32_e32 v4, 0x100, v4
	global_atomic_add v4, v3, s[6:7]
	v_add_u32_e32 v4, 0x100, v4
	global_atomic_add v4, v3, s[6:7]
	v_add_u32_e32 v4, 0x100, v4
	global_atomic_add v4, v3, s[6:7]
	v_add_u32_e32 v4, 0x100, v4
	global_atomic_add v4, v3, s[6:7]
	v_add_u32_e32 v4, 0x100, v4
	global_atomic_add v4, v3, s[6:7]
	v_add_u32_e32 v4, 0x100, v4
	global_atomic_add v4, v3, s[6:7]
	v_add_u32_e32 v4, 0x100, v4
	global_atomic_add v4, v3, s[6:7]
	v_add_u32_e32 v4, 0x100, v4
	global_atomic_add v4, v3, s[6:7]
	v_add_u32_e32 v4, 0x100, v4
	global_atomic_add v4, v3, s[6:7]
	v_add_u32_e32 v4, 0x100, v4
	global_atomic_add v4, v3, s[6:7]
	v_add_u32_e32 v4, 0x100, v4
	global_atomic_add v4, v3, s[6:7]
	v_add_u32_e32 v4, 0x100, v4
	global_atomic_add v4, v3, s[6:7]
	v_add_u32_e32 v4, 0x100, v4
	v_mov_b32_e32 v4, 0x7f000
	global_atomic_add v4, v3, s[30:31] offset:1280

.Lxb_done_11:
	s_or_b64 exec, exec, s[4:5]
	s_waitcnt lgkmcnt(0)
	s_barrier
.LBB0_2123:
	s_cmp_gt_i32 s66, 11
	s_cselect_b64 s[0:1], -1, 0
	s_cmp_lt_i32 s67, 12
	s_cselect_b64 s[2:3], -1, 0
	s_or_b64 s[0:1], s[0:1], s[2:3]
	s_and_b64 vcc, exec, s[0:1]
	s_cbranch_vccnz .LBB0_2177
	v_readlane_b32 s12, v250, 6
	s_cmpk_gt_i32 s78, 0x3ff
	v_readlane_b32 s24, v250, 18
	v_readlane_b32 s25, v250, 19
	v_readlane_b32 s26, v250, 20
	v_readlane_b32 s27, v250, 21
	v_readlane_b32 s13, v250, 7
	v_readlane_b32 s14, v250, 8
	v_readlane_b32 s15, v250, 9
	v_readlane_b32 s16, v250, 10
	v_readlane_b32 s17, v250, 11
	v_readlane_b32 s18, v250, 12
	v_readlane_b32 s19, v250, 13
	v_readlane_b32 s20, v250, 14
	v_readlane_b32 s21, v250, 15
	v_readlane_b32 s22, v250, 16
	v_readlane_b32 s23, v250, 17
	s_cbranch_scc1 .LBB0_2127
	s_add_u32 s2, s30, 0x4c000
	s_addc_u32 s3, s31, 0
	s_add_u32 s0, s30, 0xc793e00
	s_addc_u32 s1, s31, 0
	s_lshl_b32 s4, s78, 4
	s_lshl_b32 s5, s78, 3
	s_or_b32 s4, s4, 14
	s_lshl_b32 s11, s64, 4
	s_or_b32 s6, s5, 7
	s_lshl_b32 s14, s64, 3
	s_mov_b32 s9, 0
	s_waitcnt vmcnt(11)
	v_mov_b32_e32 v12, 0
	s_mov_b32 s10, 0x3a800000
	s_mov_b32 s15, 0x800000
	s_movk_i32 s16, 0x1000
	s_mov_b32 s17, s78

.LBB0_3104:
	s_cmp_gt_i32 s67, 13
	s_cbranch_scc0 .LBB0_3154
	s_waitcnt vmcnt(0)
	s_waitcnt vmcnt(63) expcnt(7) lgkmcnt(15)
	s_barrier
	s_mov_b64 s[4:5], exec
	v_readlane_b32 s2, v251, 3
	v_readlane_b32 s3, v251, 4
	s_and_b64 s[2:3], s[4:5], s[2:3]
	s_mov_b64 exec, s[2:3]
	s_cbranch_execz .Lxb_done_13
	v_mov_b32_e32 v0, 0
	s_waitcnt vmcnt(0) expcnt(0) lgkmcnt(0)
	ds_read_b32 v2, v0
	ds_read_b32 v1, v0 offset:4
	v_readlane_b32 s0, v251, 2
	v_readlane_b32 s6, v251, 5
	v_readlane_b32 s7, v251, 6
	s_lshl_b32 s0, s0, 8
	s_add_u32 s8, s6, s0
	s_addc_u32 s9, s7, 0
	v_mov_b32_e32 v3, 1
	v_mov_b32_e32 v4, 0x1000
	s_nop 4
	global_atomic_add v3, v4, v3, s[8:9] offset:1024 sc0
	buffer_inv sc1
	s_sub_u32 s10, 12, s66
	s_add_u32 s11, s10, 1
	s_waitcnt lgkmcnt(0)
	v_readfirstlane_b32 s12, v2
	v_readfirstlane_b32 s13, v1
	s_mul_i32 s14, s12, s11
	s_mul_i32 s15, s13, s11
	s_waitcnt vmcnt(0)
	v_readfirstlane_b32 s16, v3
	s_add_u32 s16, s16, 1
	s_cmp_lg_u32 s16, s14
	s_cbranch_scc1 .Lxb_wait_13
	buffer_wbl2 sc1
	s_waitcnt vmcnt(0)
	v_mov_b32_e32 v3, 1
	v_mov_b32_e32 v4, 0x7f000
	global_atomic_add v3, v4, v3, s[30:31] offset:1024 sc0
	s_waitcnt vmcnt(0)
	v_readfirstlane_b32 s16, v3
	s_add_u32 s16, s16, 1
	s_cmp_lg_u32 s16, s15
	s_cbranch_scc1 .Lxb_wait_13
	v_mov_b32_e32 v3, 1
	v_mov_b32_e32 v4, 0x2400
	global_atomic_add v4, v3, s[6:7]
	v_add_u32_e32 v4, 0x100, v4
	global_atomic_add v4, v3, s[6:7]
	v_add_u32_e32 v4, 0x100, v4
	global_atomic_add v4, v3, s[6:7]
	v_add_u32_e32 v4, 0x100, v4
	global_atomic_add v4, v3, s[6:7]
	v_add_u32_e32 v4, 0x100, v4
	global_atomic_add v4, v3, s[6:7]
	v_add_u32_e32 v4, 0x100, v4
	global_atomic_add v4, v3, s[6:7]
	v_add_u32_e32 v4, 0x100, v4
	global_atomic_add v4, v3, s[6:7]
	v_add_u32_e32 v4, 0x100, v4
	global_atomic_add v4, v3, s[6:7]
	v_add_u32_e32 v4, 0x100, v4
	global_atomic_add v4, v3, s[6:7]
	v_add_u32_e32 v4, 0x100, v4
	global_atomic_add v4, v3, s[6:7]
	v_add_u32_e32 v4, 0x100, v4
	global_atomic_add v4, v3, s[6:7]
	v_add_u32_e32 v4, 0x100, v4
	global_atomic_add v4, v3, s[6:7]
	v_add_u32_e32 v4, 0x100, v4
	global_atomic_add v4, v3, s[6:7]
	v_add_u32_e32 v4, 0x100, v4
	global_atomic_add v4, v3, s[6:7]
	v_add_u32_e32 v4, 0x100, v4
	global_atomic_add v4, v3, s[6:7]
	v_add_u32_e32 v4, 0x100, v4
	global_atomic_add v4, v3, s[6:7]
	v_add_u32_e32 v4, 0x100, v4
	v_mov_b32_e32 v4, 0x7f000
	global_atomic_add v4, v3, s[30:31] offset:1280

.Lxb_done_13:
	s_or_b64 exec, exec, s[4:5]
	s_waitcnt lgkmcnt(0)
	s_barrier
.LBB0_3154:
	s_cmp_gt_i32 s66, 13
	s_cselect_b64 s[0:1], -1, 0
	s_cmp_lt_i32 s67, 14
	s_cselect_b64 s[2:3], -1, 0
	s_or_b64 s[0:1], s[0:1], s[2:3]
	s_and_b64 vcc, exec, s[0:1]
	s_cbranch_vccnz .LBB0_3640
	s_add_u32 s42, s30, 0x7f800
	s_addc_u32 s43, s31, 0
	s_add_u32 s0, s30, 0xdf93e00
	v_writelane_b32 v250, s0, 48
	s_addc_u32 s0, s31, 0
	v_writelane_b32 v250, s0, 49
	s_add_u32 s0, s30, 0xe793e00
	s_addc_u32 s1, s31, 0
	s_add_u32 s66, s30, 0xef93e00
	v_writelane_b32 v251, s0, 61
	s_addc_u32 s67, s31, 0
	v_mov_b32_e32 v5, 0
	v_writelane_b32 v251, s1, 62
	s_add_u32 s0, s30, 0xbf93e00
	v_writelane_b32 v250, s0, 47
	s_addc_u32 s0, s31, 0
	v_writelane_b32 v250, s0, 39
	s_add_u32 s0, s30, 0x8b93e00
	s_addc_u32 s1, s31, 0
	s_add_u32 s34, s30, 0xa393e00
	s_addc_u32 s35, s31, 0
	s_add_u32 s36, s30, 0xd793e00
	s_addc_u32 s37, s31, 0
	s_add_u32 s46, s30, 0xaf93e00
	s_addc_u32 s47, s31, 0
	s_add_u32 s48, s30, 0x8393e00
	s_addc_u32 s49, s31, 0
	s_add_u32 s40, s30, 0x83e00
	s_addc_u32 s41, s31, 0
	s_add_u32 s44, s30, 0x93e00
	s_addc_u32 s45, s31, 0
	s_add_u32 s50, s30, 0x113e00
	s_addc_u32 s51, s31, 0
	s_add_u32 s52, s30, 0x9393e00
	v_writelane_b32 v251, s0, 63
	s_addc_u32 s53, s31, 0
	v_readlane_b32 s4, v251, 23
	v_writelane_b32 v250, s1, 0
	s_add_u32 s0, s30, 0xb793e00
	s_addc_u32 s1, s31, 0
	v_writelane_b32 v250, s0, 22
	v_readlane_b32 s8, v251, 27
	v_readlane_b32 s9, v251, 28
	v_writelane_b32 v250, s1, 23
	s_add_u32 s0, s28, 0x3000000
	s_addc_u32 s1, s29, 0
	v_writelane_b32 v250, s0, 24
	v_readlane_b32 s10, v251, 29
	v_readlane_b32 s11, v251, 30
	v_writelane_b32 v250, s1, 25
	s_add_u32 s0, s30, 0xc393e00
	v_writelane_b32 v250, s0, 52
	s_addc_u32 s0, s31, 0
	s_add_u32 s33, s30, 0x193e00
	s_addc_u32 s3, s31, 0
	v_writelane_b32 v250, s0, 36
	s_add_u32 s0, s30, 0x593e00
	v_writelane_b32 v250, s0, 40
	s_addc_u32 s0, s31, 0
	v_writelane_b32 v250, s0, 42
	s_add_u32 s0, s30, 0xe393e00
	v_writelane_b32 v250, s0, 26
	s_addc_u32 s0, s31, 0
	v_writelane_b32 v250, s0, 28
	s_add_u32 s0, s30, 0x993e00
	s_addc_u32 s1, s31, 0
	v_writelane_b32 v250, s0, 30
	v_readlane_b32 s12, v251, 31
	v_readlane_b32 s13, v251, 32
	v_readlane_b32 s14, v251, 33
	v_readlane_b32 s15, v251, 34
	v_writelane_b32 v250, s1, 31
	s_add_u32 s0, s30, 0xdf93e80
	v_readlane_b32 s16, v251, 35
	v_readlane_b32 s17, v251, 36
	v_readlane_b32 s18, v251, 37
	v_readlane_b32 s19, v251, 38
	s_mov_b64 s[8:9], s[12:13]
	v_writelane_b32 v250, s0, 53
	s_addc_u32 s0, s31, 0
	s_mov_b64 s[10:11], s[14:15]
	v_writelane_b32 v250, s0, 32
	s_add_u32 s0, s10, 0x3a20
	v_writelane_b32 v250, s0, 33
	s_addc_u32 s0, s11, 0
	v_writelane_b32 v250, s0, 46
	s_add_u32 s0, s30, 0xc393f80
	v_writelane_b32 v250, s0, 43
	s_addc_u32 s0, s31, 0
	v_writelane_b32 v250, s0, 44
	s_add_u32 s0, s30, 0xe393e80
	v_readlane_b32 s5, v251, 24
	v_readlane_b32 s6, v251, 25
	v_readlane_b32 s7, v251, 26
	v_writelane_b32 v251, s0, 57
	s_addc_u32 s0, s31, 0
	v_writelane_b32 v251, s0, 59
	s_add_i32 s0, 32, 0x9000
	v_writelane_b32 v250, s0, 45
	v_writelane_b32 v250, s42, 1
	v_mbcnt_lo_u32_b32 v0, -1, 0
	v_mov_b32_e32 v235, 0x3ecc95a3
	v_writelane_b32 v250, s43, 2
	v_writelane_b32 v250, s50, 3
	s_movk_i32 s65, 0x90
	v_mov_b32_e32 v236, 0x3727c5ac
	v_writelane_b32 v250, s51, 4
	v_mov_b32_e32 v237, 0x7f800000
	v_mbcnt_hi_u32_b32 v238, -1, v0
	v_mov_b32_e32 v239, 0x1000
	s_mov_b32 s95, 0
	s_mov_b64 s[38:39], 0x80
	v_writelane_b32 v250, s52, 50
	s_mov_b64 s[12:13], s[16:17]
	s_mov_b64 s[14:15], s[18:19]
	v_writelane_b32 v250, s53, 51
	s_branch .LBB0_3159

.LBB0_3590:
	v_readlane_b32 s66, v251, 55
	v_readlane_b32 s67, v251, 56
	s_cmp_gt_i32 s67, 14
	s_cbranch_scc0 .LBB0_3640
	s_waitcnt vmcnt(0)
	s_waitcnt vmcnt(63) expcnt(7) lgkmcnt(15)
	s_barrier
	s_mov_b64 s[4:5], exec
	v_readlane_b32 s2, v251, 3
	v_readlane_b32 s3, v251, 4
	s_and_b64 s[2:3], s[4:5], s[2:3]
	s_mov_b64 exec, s[2:3]
	s_cbranch_execz .Lxb_done_14
	v_mov_b32_e32 v0, 0
	s_waitcnt vmcnt(0) expcnt(0) lgkmcnt(0)
	ds_read_b32 v2, v0
	ds_read_b32 v1, v0 offset:4
	v_readlane_b32 s0, v251, 2
	v_readlane_b32 s6, v251, 5
	v_readlane_b32 s7, v251, 6
	s_lshl_b32 s0, s0, 8
	s_add_u32 s8, s6, s0
	s_addc_u32 s9, s7, 0
	v_mov_b32_e32 v3, 1
	v_mov_b32_e32 v4, 0x1000
	s_nop 4
	global_atomic_add v3, v4, v3, s[8:9] offset:1024 sc0
	buffer_inv sc1
	s_sub_u32 s10, 13, s66
	s_add_u32 s11, s10, 1
	s_waitcnt lgkmcnt(0)
	v_readfirstlane_b32 s12, v2
	v_readfirstlane_b32 s13, v1
	s_mul_i32 s14, s12, s11
	s_mul_i32 s15, s13, s11
	s_waitcnt vmcnt(0)
	v_readfirstlane_b32 s16, v3
	s_add_u32 s16, s16, 1
	s_cmp_lg_u32 s16, s14
	s_cbranch_scc1 .Lxb_wait_14
	buffer_wbl2 sc1
	s_waitcnt vmcnt(0)
	v_mov_b32_e32 v3, 1
	v_mov_b32_e32 v4, 0x7f000
	global_atomic_add v3, v4, v3, s[30:31] offset:1024 sc0
	s_waitcnt vmcnt(0)
	v_readfirstlane_b32 s16, v3
	s_add_u32 s16, s16, 1
	s_cmp_lg_u32 s16, s15
	s_cbranch_scc1 .Lxb_wait_14
	v_mov_b32_e32 v3, 1
	v_mov_b32_e32 v4, 0x2400
	global_atomic_add v4, v3, s[6:7]
	v_add_u32_e32 v4, 0x100, v4
	global_atomic_add v4, v3, s[6:7]
	v_add_u32_e32 v4, 0x100, v4
	global_atomic_add v4, v3, s[6:7]
	v_add_u32_e32 v4, 0x100, v4
	global_atomic_add v4, v3, s[6:7]
	v_add_u32_e32 v4, 0x100, v4
	global_atomic_add v4, v3, s[6:7]
	v_add_u32_e32 v4, 0x100, v4
	global_atomic_add v4, v3, s[6:7]
	v_add_u32_e32 v4, 0x100, v4
	global_atomic_add v4, v3, s[6:7]
	v_add_u32_e32 v4, 0x100, v4
	global_atomic_add v4, v3, s[6:7]
	v_add_u32_e32 v4, 0x100, v4
	global_atomic_add v4, v3, s[6:7]
	v_add_u32_e32 v4, 0x100, v4
	global_atomic_add v4, v3, s[6:7]
	v_add_u32_e32 v4, 0x100, v4
	global_atomic_add v4, v3, s[6:7]
	v_add_u32_e32 v4, 0x100, v4
	global_atomic_add v4, v3, s[6:7]
	v_add_u32_e32 v4, 0x100, v4
	global_atomic_add v4, v3, s[6:7]
	v_add_u32_e32 v4, 0x100, v4
	global_atomic_add v4, v3, s[6:7]
	v_add_u32_e32 v4, 0x100, v4
	global_atomic_add v4, v3, s[6:7]
	v_add_u32_e32 v4, 0x100, v4
	global_atomic_add v4, v3, s[6:7]
	v_add_u32_e32 v4, 0x100, v4
	v_mov_b32_e32 v4, 0x7f000
	global_atomic_add v4, v3, s[30:31] offset:1280

.Lxb_done_14:
	s_or_b64 exec, exec, s[4:5]
	s_waitcnt lgkmcnt(0)
	s_barrier
.LBB0_3640:
	s_cmp_gt_i32 s66, 14
	s_cselect_b64 s[0:1], -1, 0
	s_cmp_lt_i32 s67, 15
	s_cselect_b64 s[2:3], -1, 0
	s_or_b64 s[0:1], s[0:1], s[2:3]
	s_and_b64 vcc, exec, s[0:1]
	s_cbranch_vccnz .LBB0_3725
	s_lshr_b32 s3, s78, 3
	s_ashr_i32 s20, s64, 3
	v_readlane_b32 s36, v251, 23
	s_cmpk_gt_u32 s78, 0xff
	v_readlane_b32 s42, v251, 29
	v_readlane_b32 s43, v251, 30
	v_readlane_b32 s37, v251, 24
	v_readlane_b32 s38, v251, 25
	v_readlane_b32 s39, v251, 26
	v_readlane_b32 s40, v251, 27
	v_readlane_b32 s41, v251, 28
	v_readlane_b32 s44, v251, 31
	v_readlane_b32 s45, v251, 32
	v_readlane_b32 s46, v251, 33
	v_readlane_b32 s47, v251, 34
	v_readlane_b32 s48, v251, 35
	v_readlane_b32 s49, v251, 36
	v_readlane_b32 s50, v251, 37
	v_readlane_b32 s51, v251, 38
	s_cbranch_scc1 .LBB0_3650
	s_add_u32 s0, s30, 0xb793e00
	s_addc_u32 s1, s31, 0
	s_add_u32 s4, s30, 0x9393e00
	s_addc_u32 s5, s31, 0
	s_add_u32 s6, s30, 0x9b93e00
	s_addc_u32 s7, s31, 0
	s_add_u32 s8, s30, 0x3d93e00
	s_addc_u32 s9, s31, 0
	s_add_u32 s10, s30, 0xa393e00
	s_addc_u32 s11, s31, 0
	s_lshl_b32 s2, s78, 10
	s_and_b32 s21, s2, 0x1c00
	s_lshl_b32 s22, s3, 7
	s_lshl_b32 s23, s20, 7
	s_lshl_b32 s24, s3, 4
	s_lshl_b32 s25, s20, 4
	s_add_u32 s12, s42, 0x918
	s_addc_u32 s13, s43, 0
	v_mov_b32_e32 v137, 0
	s_mov_b32 s26, 0x8000
	s_mov_b32 s27, 0x10000
	s_mov_b32 s33, 0x18000
	s_movk_i32 s34, 0x90
	s_mov_b32 s35, 0xfffffc0
	s_mov_b64 s[14:15], 0x100
	s_mov_b32 s36, s3
	s_branch .LBB0_3644

.LBB0_3675:
	s_cmp_gt_i32 s67, 15
	s_cbranch_scc0 .LBB0_3725
	s_waitcnt vmcnt(0)
	s_waitcnt vmcnt(63) expcnt(7) lgkmcnt(15)
	s_barrier
	s_mov_b64 s[4:5], exec
	v_readlane_b32 s2, v251, 3
	v_readlane_b32 s3, v251, 4
	s_and_b64 s[2:3], s[4:5], s[2:3]
	s_mov_b64 exec, s[2:3]
	s_cbranch_execz .Lxb_done_15
	v_mov_b32_e32 v0, 0
	s_waitcnt vmcnt(0) expcnt(0) lgkmcnt(0)
	ds_read_b32 v2, v0
	ds_read_b32 v1, v0 offset:4
	v_readlane_b32 s0, v251, 2
	v_readlane_b32 s6, v251, 5
	v_readlane_b32 s7, v251, 6
	s_lshl_b32 s0, s0, 8
	s_add_u32 s8, s6, s0
	s_addc_u32 s9, s7, 0
	v_mov_b32_e32 v3, 1
	v_mov_b32_e32 v4, 0x1000
	s_nop 4
	global_atomic_add v3, v4, v3, s[8:9] offset:1024 sc0
	buffer_inv sc1
	s_sub_u32 s10, 14, s66
	s_add_u32 s11, s10, 1
	s_waitcnt lgkmcnt(0)
	v_readfirstlane_b32 s12, v2
	v_readfirstlane_b32 s13, v1
	s_mul_i32 s14, s12, s11
	s_mul_i32 s15, s13, s11
	s_waitcnt vmcnt(0)
	v_readfirstlane_b32 s16, v3
	s_add_u32 s16, s16, 1
	s_cmp_lg_u32 s16, s14
	s_cbranch_scc1 .Lxb_wait_15
	buffer_wbl2 sc1
	s_waitcnt vmcnt(0)
	v_mov_b32_e32 v3, 1
	v_mov_b32_e32 v4, 0x7f000
	global_atomic_add v3, v4, v3, s[30:31] offset:1024 sc0
	s_waitcnt vmcnt(0)
	v_readfirstlane_b32 s16, v3
	s_add_u32 s16, s16, 1
	s_cmp_lg_u32 s16, s15
	s_cbranch_scc1 .Lxb_wait_15
	v_mov_b32_e32 v3, 1
	v_mov_b32_e32 v4, 0x2400
	global_atomic_add v4, v3, s[6:7]
	v_add_u32_e32 v4, 0x100, v4
	global_atomic_add v4, v3, s[6:7]
	v_add_u32_e32 v4, 0x100, v4
	global_atomic_add v4, v3, s[6:7]
	v_add_u32_e32 v4, 0x100, v4
	global_atomic_add v4, v3, s[6:7]
	v_add_u32_e32 v4, 0x100, v4
	global_atomic_add v4, v3, s[6:7]
	v_add_u32_e32 v4, 0x100, v4
	global_atomic_add v4, v3, s[6:7]
	v_add_u32_e32 v4, 0x100, v4
	global_atomic_add v4, v3, s[6:7]
	v_add_u32_e32 v4, 0x100, v4
	global_atomic_add v4, v3, s[6:7]
	v_add_u32_e32 v4, 0x100, v4
	global_atomic_add v4, v3, s[6:7]
	v_add_u32_e32 v4, 0x100, v4
	global_atomic_add v4, v3, s[6:7]
	v_add_u32_e32 v4, 0x100, v4
	global_atomic_add v4, v3, s[6:7]
	v_add_u32_e32 v4, 0x100, v4
	global_atomic_add v4, v3, s[6:7]
	v_add_u32_e32 v4, 0x100, v4
	global_atomic_add v4, v3, s[6:7]
	v_add_u32_e32 v4, 0x100, v4
	global_atomic_add v4, v3, s[6:7]
	v_add_u32_e32 v4, 0x100, v4
	global_atomic_add v4, v3, s[6:7]
	v_add_u32_e32 v4, 0x100, v4
	global_atomic_add v4, v3, s[6:7]
	v_add_u32_e32 v4, 0x100, v4
	v_mov_b32_e32 v4, 0x7f000
	global_atomic_add v4, v3, s[30:31] offset:1280

.Lxb_done_15:
	s_or_b64 exec, exec, s[4:5]
	s_waitcnt lgkmcnt(0)
	s_barrier
.LBB0_3725:
	s_cmp_gt_i32 s66, 15
	s_cselect_b64 s[0:1], -1, 0
	s_cmp_lt_i32 s67, 16
	s_cselect_b64 s[2:3], -1, 0
	s_or_b64 s[0:1], s[0:1], s[2:3]
	s_and_b64 vcc, exec, s[0:1]
	s_cbranch_vccnz .LBB0_3801
	s_cmpk_gt_u32 s78, 0x1ff
	s_cbranch_scc1 .LBB0_3751
	s_lshl_b32 s0, s78, 3
	s_ashr_i32 s2, s64, 3
	s_and_b32 s3, s0, 56
	s_add_u32 s33, s30, 0x3e13e00
	s_addc_u32 s46, s31, 0
	s_add_u32 s4, s30, 0x5393e00
	s_addc_u32 s5, s31, 0
	s_add_u32 s47, s30, 0x9393e00
	s_addc_u32 s48, s31, 0
	s_lshr_b32 s49, s78, 3
	s_add_u32 s6, s30, 0x3e2bf80
	s_addc_u32 s7, s31, 0
	s_lshl_b32 s50, s49, 4
	s_lshl_b32 s51, s2, 4
	s_add_u32 s8, s30, 0x3e23f00
	s_addc_u32 s9, s31, 0
	s_add_u32 s10, s30, 0x3e1bf80
	s_addc_u32 s11, s31, 0
	s_add_u32 s12, s30, 0x3e1bf00
	s_addc_u32 s13, s31, 0
	s_and_b32 s0, s78, 7
	s_lshl_b32 s52, s0, 10
	s_add_u32 s14, s30, 0x3e13f00
	s_addc_u32 s15, s31, 0
	s_mov_b32 s53, 0xfffffc0
	s_movk_i32 s54, 0x110
	s_mov_b32 s55, 0xa393e00
	s_mov_b32 s17, 0
	v_mov_b32_e32 v97, 0
	s_mov_b32 s56, 0x8000
	s_mov_b32 s57, 0x10000
	s_mov_b32 s58, 0x18000
	s_movk_i32 s59, 0x90
	s_mov_b64 s[18:19], 0x100
	s_movk_i32 s60, 0x1800
	s_mov_b32 s61, s49
	s_branch .LBB0_3730

.LBB0_3751:
	s_cmp_gt_i32 s67, 16
	s_cbranch_scc0 .LBB0_3801
	s_waitcnt vmcnt(0)
	s_waitcnt vmcnt(63) expcnt(7) lgkmcnt(15)
	s_barrier
	s_mov_b64 s[4:5], exec
	v_readlane_b32 s2, v251, 3
	v_readlane_b32 s3, v251, 4
	s_and_b64 s[2:3], s[4:5], s[2:3]
	s_mov_b64 exec, s[2:3]
	s_cbranch_execz .Lxb_done_16
	v_mov_b32_e32 v0, 0
	s_waitcnt vmcnt(0) expcnt(0) lgkmcnt(0)
	ds_read_b32 v2, v0
	ds_read_b32 v1, v0 offset:4
	v_readlane_b32 s0, v251, 2
	v_readlane_b32 s6, v251, 5
	v_readlane_b32 s7, v251, 6
	s_lshl_b32 s0, s0, 8
	s_add_u32 s8, s6, s0
	s_addc_u32 s9, s7, 0
	v_mov_b32_e32 v3, 1
	v_mov_b32_e32 v4, 0x1000
	s_nop 4
	global_atomic_add v3, v4, v3, s[8:9] offset:1024 sc0
	buffer_inv sc1
	s_sub_u32 s10, 15, s66
	s_add_u32 s11, s10, 1
	s_waitcnt lgkmcnt(0)
	v_readfirstlane_b32 s12, v2
	v_readfirstlane_b32 s13, v1
	s_mul_i32 s14, s12, s11
	s_mul_i32 s15, s13, s11
	s_waitcnt vmcnt(0)
	v_readfirstlane_b32 s16, v3
	s_add_u32 s16, s16, 1
	s_cmp_lg_u32 s16, s14
	s_cbranch_scc1 .Lxb_wait_16
	buffer_wbl2 sc1
	s_waitcnt vmcnt(0)
	v_mov_b32_e32 v3, 1
	v_mov_b32_e32 v4, 0x7f000
	global_atomic_add v3, v4, v3, s[30:31] offset:1024 sc0
	s_waitcnt vmcnt(0)
	v_readfirstlane_b32 s16, v3
	s_add_u32 s16, s16, 1
	s_cmp_lg_u32 s16, s15
	s_cbranch_scc1 .Lxb_wait_16
	v_mov_b32_e32 v3, 1
	v_mov_b32_e32 v4, 0x2400
	global_atomic_add v4, v3, s[6:7]
	v_add_u32_e32 v4, 0x100, v4
	global_atomic_add v4, v3, s[6:7]
	v_add_u32_e32 v4, 0x100, v4
	global_atomic_add v4, v3, s[6:7]
	v_add_u32_e32 v4, 0x100, v4
	global_atomic_add v4, v3, s[6:7]
	v_add_u32_e32 v4, 0x100, v4
	global_atomic_add v4, v3, s[6:7]
	v_add_u32_e32 v4, 0x100, v4
	global_atomic_add v4, v3, s[6:7]
	v_add_u32_e32 v4, 0x100, v4
	global_atomic_add v4, v3, s[6:7]
	v_add_u32_e32 v4, 0x100, v4
	global_atomic_add v4, v3, s[6:7]
	v_add_u32_e32 v4, 0x100, v4
	global_atomic_add v4, v3, s[6:7]
	v_add_u32_e32 v4, 0x100, v4
	global_atomic_add v4, v3, s[6:7]
	v_add_u32_e32 v4, 0x100, v4
	global_atomic_add v4, v3, s[6:7]
	v_add_u32_e32 v4, 0x100, v4
	global_atomic_add v4, v3, s[6:7]
	v_add_u32_e32 v4, 0x100, v4
	global_atomic_add v4, v3, s[6:7]
	v_add_u32_e32 v4, 0x100, v4
	global_atomic_add v4, v3, s[6:7]
	v_add_u32_e32 v4, 0x100, v4
	global_atomic_add v4, v3, s[6:7]
	v_add_u32_e32 v4, 0x100, v4
	global_atomic_add v4, v3, s[6:7]
	v_add_u32_e32 v4, 0x100, v4
	v_mov_b32_e32 v4, 0x7f000
	global_atomic_add v4, v3, s[30:31] offset:1280

.Lxb_done_16:
	s_or_b64 exec, exec, s[4:5]
	s_waitcnt lgkmcnt(0)
	s_barrier
.LBB0_3801:
	s_cmp_gt_i32 s66, 16
	s_cselect_b64 s[0:1], -1, 0
	s_cmp_lt_i32 s67, 17
	s_cselect_b64 s[2:3], -1, 0
	s_or_b64 s[0:1], s[0:1], s[2:3]
	s_and_b64 vcc, exec, s[0:1]
	s_cbranch_vccnz .LBB0_3867
	s_cmpk_gt_u32 s78, 0x1ff
	s_cbranch_scc1 .LBB0_3817
	s_lshl_b32 s0, s78, 3
	s_ashr_i32 s2, s64, 3
	s_and_b32 s3, s0, 56
	s_add_u32 s4, s30, 0x9393e00
	s_addc_u32 s5, s31, 0
	s_add_u32 s6, s30, 0x4113e00
	s_addc_u32 s7, s31, 0
	s_cmp_lt_u32 s3, 32
	s_cselect_b64 s[8:9], -1, 0
	s_add_u32 s17, s28, 0x1000000
	s_addc_u32 s19, s29, 0
	s_lshl_b32 s0, s78, 10
	s_lshr_b32 s26, s78, 3
	s_and_b32 s34, s0, 0x1c00
	v_mbcnt_lo_u32_b32 v0, -1, 0
	s_lshl_b32 s27, s26, 4
	s_lshl_b32 s33, s2, 4
	s_or_b32 s35, s34, 24
	s_or_b32 s36, s34, 16
	s_or_b32 s37, s34, 8
	v_mov_b32_e32 v97, 0
	s_mov_b32 s38, 0x10000
	s_mov_b32 s11, 0
	s_mov_b32 s39, 0x20000
	s_mov_b32 s40, 0x30000
	s_movk_i32 s41, 0x90
	s_mov_b32 s42, 0xfffffc0
	s_mov_b32 s43, 0x9393000
	s_mov_b32 s44, 0x93a3000
	s_mov_b32 s45, 0x93b3000
	s_mov_b32 s46, 0x93c3000
	s_mov_b32 s47, 0x4113000
	s_mov_b32 s48, 0x4123000
	s_mov_b32 s49, 0x4133000
	s_mov_b32 s50, 0x4143000
	s_mov_b64 s[12:13], 0x100
	s_mov_b64 s[14:15], 0x2000
	s_movk_i32 s51, 0x2000
	s_movk_i32 s52, 0x210
	s_mov_b32 s16, 0x3a800000
	s_mov_b32 s53, 0x800000
	s_mov_b32 s18, 0x3fb504f3
	s_mov_b32 s54, 0xd793000
	s_mov_b32 s55, 0x8000
	s_mov_b32 s56, 0x18000
	s_mov_b64 s[20:21], 0x20000
	v_mbcnt_hi_u32_b32 v102, -1, v0
	s_mov_b32 s57, s26
	s_branch .LBB0_3805

.LBB0_3817:
	s_cmp_gt_i32 s67, 17
	s_cbranch_scc0 .LBB0_3867
	s_waitcnt vmcnt(0)
	s_waitcnt vmcnt(63) expcnt(7) lgkmcnt(15)
	s_barrier
	s_mov_b64 s[4:5], exec
	v_readlane_b32 s2, v251, 3
	v_readlane_b32 s3, v251, 4
	s_and_b64 s[2:3], s[4:5], s[2:3]
	s_mov_b64 exec, s[2:3]
	s_cbranch_execz .Lxb_done_17
	v_mov_b32_e32 v0, 0
	s_waitcnt vmcnt(0) expcnt(0) lgkmcnt(0)
	ds_read_b32 v2, v0
	ds_read_b32 v1, v0 offset:4
	v_readlane_b32 s0, v251, 2
	v_readlane_b32 s6, v251, 5
	v_readlane_b32 s7, v251, 6
	s_lshl_b32 s0, s0, 8
	s_add_u32 s8, s6, s0
	s_addc_u32 s9, s7, 0
	v_mov_b32_e32 v3, 1
	v_mov_b32_e32 v4, 0x1000
	s_nop 4
	global_atomic_add v3, v4, v3, s[8:9] offset:1024 sc0
	buffer_inv sc1
	s_sub_u32 s10, 16, s66
	s_add_u32 s11, s10, 1
	s_waitcnt lgkmcnt(0)
	v_readfirstlane_b32 s12, v2
	v_readfirstlane_b32 s13, v1
	s_mul_i32 s14, s12, s11
	s_mul_i32 s15, s13, s11
	s_waitcnt vmcnt(0)
	v_readfirstlane_b32 s16, v3
	s_add_u32 s16, s16, 1
	s_cmp_lg_u32 s16, s14
	s_cbranch_scc1 .Lxb_wait_17
	buffer_wbl2 sc1
	s_waitcnt vmcnt(0)
	v_mov_b32_e32 v3, 1
	v_mov_b32_e32 v4, 0x7f000
	global_atomic_add v3, v4, v3, s[30:31] offset:1024 sc0
	s_waitcnt vmcnt(0)
	v_readfirstlane_b32 s16, v3
	s_add_u32 s16, s16, 1
	s_cmp_lg_u32 s16, s15
	s_cbranch_scc1 .Lxb_wait_17
	v_mov_b32_e32 v3, 1
	v_mov_b32_e32 v4, 0x2400
	global_atomic_add v4, v3, s[6:7]
	v_add_u32_e32 v4, 0x100, v4
	global_atomic_add v4, v3, s[6:7]
	v_add_u32_e32 v4, 0x100, v4
	global_atomic_add v4, v3, s[6:7]
	v_add_u32_e32 v4, 0x100, v4
	global_atomic_add v4, v3, s[6:7]
	v_add_u32_e32 v4, 0x100, v4
	global_atomic_add v4, v3, s[6:7]
	v_add_u32_e32 v4, 0x100, v4
	global_atomic_add v4, v3, s[6:7]
	v_add_u32_e32 v4, 0x100, v4
	global_atomic_add v4, v3, s[6:7]
	v_add_u32_e32 v4, 0x100, v4
	global_atomic_add v4, v3, s[6:7]
	v_add_u32_e32 v4, 0x100, v4
	global_atomic_add v4, v3, s[6:7]
	v_add_u32_e32 v4, 0x100, v4
	global_atomic_add v4, v3, s[6:7]
	v_add_u32_e32 v4, 0x100, v4
	global_atomic_add v4, v3, s[6:7]
	v_add_u32_e32 v4, 0x100, v4
	global_atomic_add v4, v3, s[6:7]
	v_add_u32_e32 v4, 0x100, v4
	global_atomic_add v4, v3, s[6:7]
	v_add_u32_e32 v4, 0x100, v4
	global_atomic_add v4, v3, s[6:7]
	v_add_u32_e32 v4, 0x100, v4
	global_atomic_add v4, v3, s[6:7]
	v_add_u32_e32 v4, 0x100, v4
	global_atomic_add v4, v3, s[6:7]
	v_add_u32_e32 v4, 0x100, v4
	v_mov_b32_e32 v4, 0x7f000
	global_atomic_add v4, v3, s[30:31] offset:1280

.Lxb_done_17:
	s_or_b64 exec, exec, s[4:5]
	s_waitcnt lgkmcnt(0)
	s_barrier
.LBB0_3867:
	s_cmp_gt_i32 s66, 17
	s_cselect_b64 s[0:1], -1, 0
	s_cmp_lt_i32 s67, 18
	s_cselect_b64 s[2:3], -1, 0
	s_or_b64 s[0:1], s[0:1], s[2:3]
	s_and_b64 vcc, exec, s[0:1]
	s_cbranch_vccnz .LBB0_3921
	s_cmpk_gt_i32 s78, 0x3ff
	s_cbranch_scc1 .LBB0_3871
	v_readlane_b32 s0, v250, 6
	v_readlane_b32 s1, v250, 7
	s_add_u32 s0, s0, 0x1000
	v_readlane_b32 s2, v250, 8
	v_readlane_b32 s4, v250, 10
	s_addc_u32 s1, s1, 0
	v_readlane_b32 s3, v250, 9
	v_readlane_b32 s5, v250, 11
	s_add_u32 s4, s2, 0x1000
	s_addc_u32 s5, s3, 0
	s_add_u32 s2, s30, 0x5c000
	v_readlane_b32 s6, v250, 12
	s_addc_u32 s3, s31, 0
	v_readlane_b32 s7, v250, 13
	s_add_u32 s6, s30, 0xab93e00
	v_readlane_b32 s15, v250, 21
	s_addc_u32 s7, s31, 0
	v_readlane_b32 s8, v250, 14
	v_readlane_b32 s9, v250, 15
	s_add_u32 s15, s30, 0xd793e00
	v_readlane_b32 s10, v250, 16
	v_readlane_b32 s13, v250, 19
	v_readlane_b32 s14, v250, 20
	s_addc_u32 s18, s31, 0
	s_lshl_b32 s8, s78, 4
	s_lshl_b32 s9, s78, 3
	s_or_b32 s8, s8, 14
	s_lshl_b32 s19, s64, 4
	s_or_b32 s10, s9, 7
	s_lshl_b32 s20, s64, 3
	s_mov_b32 s13, 0
	s_waitcnt vmcnt(11)
	v_mov_b32_e32 v12, 0
	s_mov_b32 s14, 0x3a800000
	s_mov_b32 s21, 0x800000
	s_movk_i32 s22, 0x4000
	s_movk_i32 s23, 0x3000
	s_mov_b32 s24, s78
	v_readlane_b32 s11, v250, 17
	v_readlane_b32 s12, v250, 18

.LBB0_3931:
	s_cmp_gt_i32 s67, 19
	s_cbranch_scc0 .LBB0_3981
	s_waitcnt vmcnt(0)
	s_waitcnt vmcnt(63) expcnt(7) lgkmcnt(15)
	s_barrier
	s_mov_b64 s[4:5], exec
	v_readlane_b32 s2, v251, 3
	v_readlane_b32 s3, v251, 4
	s_and_b64 s[2:3], s[4:5], s[2:3]
	s_mov_b64 exec, s[2:3]
	s_cbranch_execz .Lxb_done_19
	v_mov_b32_e32 v0, 0
	s_waitcnt vmcnt(0) expcnt(0) lgkmcnt(0)
	ds_read_b32 v2, v0
	ds_read_b32 v1, v0 offset:4
	v_readlane_b32 s0, v251, 2
	v_readlane_b32 s6, v251, 5
	v_readlane_b32 s7, v251, 6
	s_lshl_b32 s0, s0, 8
	s_add_u32 s8, s6, s0
	s_addc_u32 s9, s7, 0
	v_mov_b32_e32 v3, 1
	v_mov_b32_e32 v4, 0x1000
	s_nop 4
	global_atomic_add v3, v4, v3, s[8:9] offset:1024 sc0
	buffer_inv sc1
	s_sub_u32 s10, 18, s66
	s_add_u32 s11, s10, 1
	s_waitcnt lgkmcnt(0)
	v_readfirstlane_b32 s12, v2
	v_readfirstlane_b32 s13, v1
	s_mul_i32 s14, s12, s11
	s_mul_i32 s15, s13, s11
	s_waitcnt vmcnt(0)
	v_readfirstlane_b32 s16, v3
	s_add_u32 s16, s16, 1
	s_cmp_lg_u32 s16, s14
	s_cbranch_scc1 .Lxb_wait_19
	buffer_wbl2 sc1
	s_waitcnt vmcnt(0)
	v_mov_b32_e32 v3, 1
	v_mov_b32_e32 v4, 0x7f000
	global_atomic_add v3, v4, v3, s[30:31] offset:1024 sc0
	s_waitcnt vmcnt(0)
	v_readfirstlane_b32 s16, v3
	s_add_u32 s16, s16, 1
	s_cmp_lg_u32 s16, s15
	s_cbranch_scc1 .Lxb_wait_19
	v_mov_b32_e32 v3, 1
	v_mov_b32_e32 v4, 0x2400
	global_atomic_add v4, v3, s[6:7]
	v_add_u32_e32 v4, 0x100, v4
	global_atomic_add v4, v3, s[6:7]
	v_add_u32_e32 v4, 0x100, v4
	global_atomic_add v4, v3, s[6:7]
	v_add_u32_e32 v4, 0x100, v4
	global_atomic_add v4, v3, s[6:7]
	v_add_u32_e32 v4, 0x100, v4
	global_atomic_add v4, v3, s[6:7]
	v_add_u32_e32 v4, 0x100, v4
	global_atomic_add v4, v3, s[6:7]
	v_add_u32_e32 v4, 0x100, v4
	global_atomic_add v4, v3, s[6:7]
	v_add_u32_e32 v4, 0x100, v4
	global_atomic_add v4, v3, s[6:7]
	v_add_u32_e32 v4, 0x100, v4
	global_atomic_add v4, v3, s[6:7]
	v_add_u32_e32 v4, 0x100, v4
	global_atomic_add v4, v3, s[6:7]
	v_add_u32_e32 v4, 0x100, v4
	global_atomic_add v4, v3, s[6:7]
	v_add_u32_e32 v4, 0x100, v4
	global_atomic_add v4, v3, s[6:7]
	v_add_u32_e32 v4, 0x100, v4
	global_atomic_add v4, v3, s[6:7]
	v_add_u32_e32 v4, 0x100, v4
	global_atomic_add v4, v3, s[6:7]
	v_add_u32_e32 v4, 0x100, v4
	global_atomic_add v4, v3, s[6:7]
	v_add_u32_e32 v4, 0x100, v4
	global_atomic_add v4, v3, s[6:7]
	v_add_u32_e32 v4, 0x100, v4
	v_mov_b32_e32 v4, 0x7f000
	global_atomic_add v4, v3, s[30:31] offset:1280

.Lxb_done_19:
	s_or_b64 exec, exec, s[4:5]
	s_waitcnt lgkmcnt(0)
	s_barrier
.LBB0_3981:
	s_cmp_gt_i32 s66, 19
	s_cselect_b64 s[0:1], -1, 0
	s_cmp_lt_i32 s67, 20
	s_cselect_b64 s[2:3], -1, 0
	s_or_b64 s[0:1], s[0:1], s[2:3]
	s_and_b64 vcc, exec, s[0:1]
	s_cbranch_vccnz .LBB0_4046
	s_cmpk_gt_i32 s78, 0x1ff
	s_cbranch_scc1 .LBB0_3996
	v_readlane_b32 s8, v250, 6
	v_readlane_b32 s14, v250, 12
	v_readlane_b32 s15, v250, 13
	s_add_u32 s0, s14, 0x10800
	s_addc_u32 s1, s15, 0
	s_add_u32 s4, s14, 0x13400
	s_addc_u32 s5, s15, 0
	s_add_u32 s6, s14, 0x16000
	s_addc_u32 s7, s15, 0
	v_readlane_b32 s9, v250, 7
	s_add_u32 s8, s14, 0x18c00
	v_readlane_b32 s10, v250, 8
	s_addc_u32 s9, s15, 0
	v_readlane_b32 s11, v250, 9
	s_add_u32 s10, s14, 0x1b800
	v_readlane_b32 s12, v250, 10
	s_addc_u32 s11, s15, 0
	v_readlane_b32 s13, v250, 11
	s_add_u32 s12, s14, 0x1e400
	v_readlane_b32 s16, v250, 14
	s_addc_u32 s13, s15, 0
	v_readlane_b32 s17, v250, 15
	s_add_u32 s14, s16, 0x5800
	s_addc_u32 s15, s17, 0
	s_add_u32 s16, s16, 0x8400
	s_addc_u32 s17, s17, 0
	s_add_u32 s2, s30, 0x5393e00
	s_addc_u32 s3, s31, 0
	s_lshl_b32 s24, s78, 4
	s_lshl_b32 s25, s64, 4
	s_movk_i32 s26, 0xb0
	s_movk_i32 s27, 0xe0
	s_movk_i32 s33, 0xff
	s_mov_b32 s34, 0xab95000
	v_mov_b32_e32 v0, 0
	s_mov_b32 s35, s78
	v_readlane_b32 s18, v250, 16
	v_readlane_b32 s19, v250, 17
	v_readlane_b32 s20, v250, 18
	v_readlane_b32 s21, v250, 19
	v_readlane_b32 s22, v250, 20
	v_readlane_b32 s23, v250, 21
	s_branch .LBB0_3985

.LBB0_3996:
	s_cmp_gt_i32 s67, 20
	s_cbranch_scc0 .LBB0_4046
	s_waitcnt vmcnt(0)
	s_waitcnt vmcnt(63) expcnt(7) lgkmcnt(15)
	s_barrier
	s_mov_b64 s[4:5], exec
	v_readlane_b32 s2, v251, 3
	v_readlane_b32 s3, v251, 4
	s_and_b64 s[2:3], s[4:5], s[2:3]
	s_mov_b64 exec, s[2:3]
	s_cbranch_execz .Lxb_done_20
	v_mov_b32_e32 v0, 0
	s_waitcnt vmcnt(0) expcnt(0) lgkmcnt(0)
	ds_read_b32 v2, v0
	ds_read_b32 v1, v0 offset:4
	v_readlane_b32 s0, v251, 2
	v_readlane_b32 s6, v251, 5
	v_readlane_b32 s7, v251, 6
	s_lshl_b32 s0, s0, 8
	s_add_u32 s8, s6, s0
	s_addc_u32 s9, s7, 0
	v_mov_b32_e32 v3, 1
	v_mov_b32_e32 v4, 0x1000
	s_nop 4
	global_atomic_add v3, v4, v3, s[8:9] offset:1024 sc0
	buffer_inv sc1
	s_sub_u32 s10, 19, s66
	s_add_u32 s11, s10, 1
	s_waitcnt lgkmcnt(0)
	v_readfirstlane_b32 s12, v2
	v_readfirstlane_b32 s13, v1
	s_mul_i32 s14, s12, s11
	s_mul_i32 s15, s13, s11
	s_waitcnt vmcnt(0)
	v_readfirstlane_b32 s16, v3
	s_add_u32 s16, s16, 1
	s_cmp_lg_u32 s16, s14
	s_cbranch_scc1 .Lxb_wait_20
	buffer_wbl2 sc1
	s_waitcnt vmcnt(0)
	v_mov_b32_e32 v3, 1
	v_mov_b32_e32 v4, 0x7f000
	global_atomic_add v3, v4, v3, s[30:31] offset:1024 sc0
	s_waitcnt vmcnt(0)
	v_readfirstlane_b32 s16, v3
	s_add_u32 s16, s16, 1
	s_cmp_lg_u32 s16, s15
	s_cbranch_scc1 .Lxb_wait_20
	v_mov_b32_e32 v3, 1
	v_mov_b32_e32 v4, 0x2400
	global_atomic_add v4, v3, s[6:7]
	v_add_u32_e32 v4, 0x100, v4
	global_atomic_add v4, v3, s[6:7]
	v_add_u32_e32 v4, 0x100, v4
	global_atomic_add v4, v3, s[6:7]
	v_add_u32_e32 v4, 0x100, v4
	global_atomic_add v4, v3, s[6:7]
	v_add_u32_e32 v4, 0x100, v4
	global_atomic_add v4, v3, s[6:7]
	v_add_u32_e32 v4, 0x100, v4
	global_atomic_add v4, v3, s[6:7]
	v_add_u32_e32 v4, 0x100, v4
	global_atomic_add v4, v3, s[6:7]
	v_add_u32_e32 v4, 0x100, v4
	global_atomic_add v4, v3, s[6:7]
	v_add_u32_e32 v4, 0x100, v4
	global_atomic_add v4, v3, s[6:7]
	v_add_u32_e32 v4, 0x100, v4
	global_atomic_add v4, v3, s[6:7]
	v_add_u32_e32 v4, 0x100, v4
	global_atomic_add v4, v3, s[6:7]
	v_add_u32_e32 v4, 0x100, v4
	global_atomic_add v4, v3, s[6:7]
	v_add_u32_e32 v4, 0x100, v4
	global_atomic_add v4, v3, s[6:7]
	v_add_u32_e32 v4, 0x100, v4
	global_atomic_add v4, v3, s[6:7]
	v_add_u32_e32 v4, 0x100, v4
	global_atomic_add v4, v3, s[6:7]
	v_add_u32_e32 v4, 0x100, v4
	global_atomic_add v4, v3, s[6:7]
	v_add_u32_e32 v4, 0x100, v4
	v_mov_b32_e32 v4, 0x7f000
	global_atomic_add v4, v3, s[30:31] offset:1280

.Lxb_done_20:
	s_or_b64 exec, exec, s[4:5]
	s_waitcnt lgkmcnt(0)
	s_barrier
.LBB0_4046:
	s_cmp_gt_i32 s66, 20
	s_cselect_b64 s[0:1], -1, 0
	s_cmp_lt_i32 s67, 21
	s_cselect_b64 s[2:3], -1, 0
	s_or_b64 s[0:1], s[0:1], s[2:3]
	s_and_b64 vcc, exec, s[0:1]
	s_cbranch_vccnz .LBB0_4112
	s_cmpk_gt_u32 s78, 0x1ff
	s_cbranch_scc1 .LBB0_4062
	s_lshl_b32 s0, s78, 3
	s_ashr_i32 s2, s64, 3
	s_and_b32 s3, s0, 56
	s_add_u32 s0, s30, 0xab93e00
	s_addc_u32 s1, s31, 0
	s_add_u32 s12, s30, 0x4e13e00
	s_addc_u32 s13, s31, 0
	s_cmp_lt_u32 s3, 32
	s_cselect_b64 s[4:5], -1, 0
	s_add_u32 s19, s30, 0xd793e00
	s_addc_u32 s21, s31, 0
	s_add_u32 s33, s30, 0xe793e00
	s_addc_u32 s34, s31, 0
	v_readlane_b32 s36, v250, 6
	v_readlane_b32 s37, v250, 7
	s_add_u32 s6, s36, 0x1000
	v_readlane_b32 s38, v250, 8
	s_addc_u32 s7, s37, 0
	v_readlane_b32 s39, v250, 9
	s_add_u32 s8, s38, 0x1000
	s_addc_u32 s9, s39, 0
	s_lshl_b32 s10, s78, 10
	v_readlane_b32 s40, v250, 10
	v_readlane_b32 s41, v250, 11
	s_lshr_b32 s35, s78, 3
	s_and_b32 s38, s10, 0x1c00
	s_lshl_b32 s36, s35, 4
	s_lshl_b32 s37, s2, 4
	s_or_b32 s39, s38, 24
	s_or_b32 s40, s38, 16
	s_or_b32 s41, s38, 8
	v_readlane_b32 s42, v250, 12
	v_readlane_b32 s43, v250, 13
	v_readlane_b32 s44, v250, 14
	v_readlane_b32 s45, v250, 15
	v_readlane_b32 s46, v250, 16
	v_readlane_b32 s47, v250, 17
	v_readlane_b32 s48, v250, 18
	v_readlane_b32 s49, v250, 19
	v_readlane_b32 s50, v250, 20
	v_readlane_b32 s51, v250, 21
	s_add_u32 s10, s28, 8
	v_mbcnt_lo_u32_b32 v0, -1, 0
	s_addc_u32 s11, s29, 0
	s_movk_i32 s42, 0x1600
	v_mov_b64_e32 v[96:97], s[0:1]
	v_mov_b32_e32 v99, 0
	v_mov_b64_e32 v[100:101], s[12:13]
	s_mov_b32 s43, 0x2c000
	s_mov_b32 s13, 0
	s_mov_b32 s44, 0x58000
	s_mov_b32 s45, 0x84000
	s_movk_i32 s46, 0x90
	s_mov_b32 s47, 0xfffffc0
	v_mov_b64_e32 v[102:103], s[30:31]
	s_mov_b32 s48, 0xab93000
	s_mov_b32 s49, 0xabbf000
	s_mov_b32 s50, 0xabeb000
	s_mov_b32 s51, 0xac17000
	s_mov_b32 s52, 0x4e13000
	s_mov_b32 s53, 0x4e3f000
	s_mov_b32 s54, 0x4e6b000
	s_mov_b32 s55, 0x4e97000
	s_mov_b64 s[14:15], 0x100
	s_mov_b64 s[16:17], 0x5000
	s_movk_i32 s56, 0x5000
	s_movk_i32 s57, 0x210
	s_mov_b32 s18, 0x3a800000
	s_mov_b32 s58, 0x800000
	s_mov_b32 s20, 0x3fb504f3
	s_mov_b32 s59, 0x8000
	s_mov_b32 s60, 0x10000
	s_mov_b32 s61, 0x18000
	s_mov_b64 s[22:23], 0x20000
	v_mbcnt_hi_u32_b32 v108, -1, v0
	s_mov_b32 s62, s35
	s_branch .LBB0_4050

.LBB0_4062:
	v_readlane_b32 s66, v251, 55
	v_readlane_b32 s67, v251, 56
	s_cmp_gt_i32 s67, 21
	s_cbranch_scc0 .LBB0_4112
	s_waitcnt vmcnt(0)
	s_waitcnt vmcnt(63) expcnt(7) lgkmcnt(15)
	s_barrier
	s_mov_b64 s[4:5], exec
	v_readlane_b32 s2, v251, 3
	v_readlane_b32 s3, v251, 4
	s_and_b64 s[2:3], s[4:5], s[2:3]
	s_mov_b64 exec, s[2:3]
	s_cbranch_execz .Lxb_done_21
	v_mov_b32_e32 v0, 0
	s_waitcnt vmcnt(0) expcnt(0) lgkmcnt(0)
	ds_read_b32 v2, v0
	ds_read_b32 v1, v0 offset:4
	v_readlane_b32 s0, v251, 2
	v_readlane_b32 s6, v251, 5
	v_readlane_b32 s7, v251, 6
	s_lshl_b32 s0, s0, 8
	s_add_u32 s8, s6, s0
	s_addc_u32 s9, s7, 0
	v_mov_b32_e32 v3, 1
	v_mov_b32_e32 v4, 0x1000
	s_nop 4
	global_atomic_add v3, v4, v3, s[8:9] offset:1024 sc0
	buffer_inv sc1
	s_sub_u32 s10, 20, s66
	s_add_u32 s11, s10, 1
	s_waitcnt lgkmcnt(0)
	v_readfirstlane_b32 s12, v2
	v_readfirstlane_b32 s13, v1
	s_mul_i32 s14, s12, s11
	s_mul_i32 s15, s13, s11
	s_waitcnt vmcnt(0)
	v_readfirstlane_b32 s16, v3
	s_add_u32 s16, s16, 1
	s_cmp_lg_u32 s16, s14
	s_cbranch_scc1 .Lxb_wait_21
	buffer_wbl2 sc1
	s_waitcnt vmcnt(0)
	v_mov_b32_e32 v3, 1
	v_mov_b32_e32 v4, 0x7f000
	global_atomic_add v3, v4, v3, s[30:31] offset:1024 sc0
	s_waitcnt vmcnt(0)
	v_readfirstlane_b32 s16, v3
	s_add_u32 s16, s16, 1
	s_cmp_lg_u32 s16, s15
	s_cbranch_scc1 .Lxb_wait_21
	v_mov_b32_e32 v3, 1
	v_mov_b32_e32 v4, 0x2400
	global_atomic_add v4, v3, s[6:7]
	v_add_u32_e32 v4, 0x100, v4
	global_atomic_add v4, v3, s[6:7]
	v_add_u32_e32 v4, 0x100, v4
	global_atomic_add v4, v3, s[6:7]
	v_add_u32_e32 v4, 0x100, v4
	global_atomic_add v4, v3, s[6:7]
	v_add_u32_e32 v4, 0x100, v4
	global_atomic_add v4, v3, s[6:7]
	v_add_u32_e32 v4, 0x100, v4
	global_atomic_add v4, v3, s[6:7]
	v_add_u32_e32 v4, 0x100, v4
	global_atomic_add v4, v3, s[6:7]
	v_add_u32_e32 v4, 0x100, v4
	global_atomic_add v4, v3, s[6:7]
	v_add_u32_e32 v4, 0x100, v4
	global_atomic_add v4, v3, s[6:7]
	v_add_u32_e32 v4, 0x100, v4
	global_atomic_add v4, v3, s[6:7]
	v_add_u32_e32 v4, 0x100, v4
	global_atomic_add v4, v3, s[6:7]
	v_add_u32_e32 v4, 0x100, v4
	global_atomic_add v4, v3, s[6:7]
	v_add_u32_e32 v4, 0x100, v4
	global_atomic_add v4, v3, s[6:7]
	v_add_u32_e32 v4, 0x100, v4
	global_atomic_add v4, v3, s[6:7]
	v_add_u32_e32 v4, 0x100, v4
	global_atomic_add v4, v3, s[6:7]
	v_add_u32_e32 v4, 0x100, v4
	global_atomic_add v4, v3, s[6:7]
	v_add_u32_e32 v4, 0x100, v4
	v_mov_b32_e32 v4, 0x7f000
	global_atomic_add v4, v3, s[30:31] offset:1280

.Lxb_done_21:
	s_or_b64 exec, exec, s[4:5]
	s_waitcnt lgkmcnt(0)
	s_barrier
.LBB0_4112:
	s_cmp_gt_i32 s66, 21
	s_cselect_b64 s[0:1], -1, 0
	s_cmp_lt_i32 s67, 22
	s_cselect_b64 s[2:3], -1, 0
	s_or_b64 s[0:1], s[0:1], s[2:3]
	s_and_b64 vcc, exec, s[0:1]
	s_cbranch_vccnz .LBB0_4166
	s_cmpk_gt_i32 s78, 0x3ff
	s_cbranch_scc1 .LBB0_4116
	v_readlane_b32 s4, v250, 6
	s_add_u32 s2, s30, 0x6c000
	v_readlane_b32 s12, v250, 14
	v_readlane_b32 s13, v250, 15
	v_readlane_b32 s14, v250, 16
	v_readlane_b32 s15, v250, 17
	v_readlane_b32 s16, v250, 18
	v_readlane_b32 s17, v250, 19
	s_addc_u32 s3, s31, 0
	v_readlane_b32 s18, v250, 20
	v_readlane_b32 s19, v250, 21
	s_mov_b64 s[12:13], s[16:17]
	s_add_u32 s0, s12, 0x1000
	s_mov_b64 s[14:15], s[18:19]
	s_addc_u32 s1, s13, 0
	v_readlane_b32 s5, v250, 7
	v_readlane_b32 s6, v250, 8
	v_readlane_b32 s7, v250, 9
	s_add_u32 s4, s14, 0x1000
	v_readlane_b32 s8, v250, 10
	v_readlane_b32 s10, v250, 12
	v_readlane_b32 s11, v250, 13
	s_addc_u32 s5, s15, 0
	s_lshl_b32 s6, s78, 3
	s_lshl_b32 s7, s78, 4
	s_or_b32 s6, s6, 7
	s_lshl_b32 s11, s64, 3
	s_or_b32 s8, s7, 14
	s_lshl_b32 s14, s64, 4
	s_waitcnt vmcnt(11)
	v_mov_b32_e32 v10, 0
	s_mov_b32 s10, 0x3a800000
	s_mov_b32 s15, 0x800000
	v_readlane_b32 s9, v250, 11
